# nt hints extended to more stream-once accesses: split-K partial loads and final stores in the row phases, SCAN's chunk loads and state stores, the f32 weight loads of the ADA phase (w_ada and the fast
# speedup vs baseline: 1.0281x; 1.0043x over previous
.LBB0_215:
	s_or_b64 exec, exec, s[8:9]
	v_add_u32_e32 v80, s26, v78
	v_min_i32_e32 v28, 0x47f, v80
	v_bfe_u32 v79, v128, 4, 2
	v_lshlrev_b32_e32 v81, 4, v28
	v_and_b32_e32 v30, 15, v128
	v_mul_u32_u24_e32 v28, 0x24000, v79
	v_or_b32_e32 v56, v81, v30
	v_lshlrev_b32_e32 v28, 2, v28
	v_mov_b32_e32 v29, 0
	v_lshl_add_u64 v[28:29], s[30:31], 0, v[28:29]
	v_ashrrev_i32_e32 v57, 31, v56
	v_lshl_add_u64 v[34:35], v[56:57], 2, v[28:29]
	s_mov_b32 s9, 0x12000
	v_add_co_u32_e32 v36, vcc, s9, v34
	s_mov_b32 s8, 0x24000
	s_nop 0
	v_addc_co_u32_e32 v37, vcc, 0, v35, vcc
	v_add_co_u32_e32 v38, vcc, s8, v34
	s_mov_b32 s8, 0x36000
	s_nop 0
	v_addc_co_u32_e32 v39, vcc, 0, v35, vcc
	v_add_co_u32_e32 v40, vcc, s8, v34
	s_mov_b32 s8, 0x48000
	s_nop 0
	v_addc_co_u32_e32 v41, vcc, 0, v35, vcc
	v_add_co_u32_e32 v42, vcc, s8, v34
	s_mov_b32 s8, 0x5a000
	s_nop 0
	v_addc_co_u32_e32 v43, vcc, 0, v35, vcc
	v_add_co_u32_e32 v44, vcc, s8, v34
	s_mov_b32 s8, 0x6c000
	s_nop 0
	v_addc_co_u32_e32 v45, vcc, 0, v35, vcc
	v_add_co_u32_e32 v46, vcc, s8, v34
	s_mov_b32 s8, 0x7e000
	s_nop 0
	v_addc_co_u32_e32 v47, vcc, 0, v35, vcc
	v_add_co_u32_e32 v48, vcc, s8, v34
	s_mov_b32 s8, 0x240000
	s_nop 0
	v_addc_co_u32_e32 v49, vcc, 0, v35, vcc
	global_load_dword v82, v[34:35], off nt
	global_load_dword v83, v[36:37], off nt
	global_load_dword v84, v[38:39], off nt
	global_load_dword v85, v[40:41], off nt
	global_load_dword v86, v[42:43], off nt
	global_load_dword v87, v[44:45], off nt
	global_load_dword v88, v[46:47], off nt
	global_load_dword v89, v[48:49], off nt
	v_add_co_u32_e32 v36, vcc, s8, v34
	s_mov_b32 s8, 0x252000
	s_nop 0
	v_addc_co_u32_e32 v37, vcc, 0, v35, vcc
	v_add_co_u32_e32 v38, vcc, s8, v34
	s_mov_b32 s8, 0x264000
	s_nop 0
	v_addc_co_u32_e32 v39, vcc, 0, v35, vcc
	v_add_co_u32_e32 v40, vcc, s8, v34
	s_mov_b32 s8, 0x276000
	s_nop 0
	v_addc_co_u32_e32 v41, vcc, 0, v35, vcc
	v_add_co_u32_e32 v42, vcc, s8, v34
	s_mov_b32 s8, 0x288000
	s_nop 0
	v_addc_co_u32_e32 v43, vcc, 0, v35, vcc
	v_add_co_u32_e32 v44, vcc, s8, v34
	s_mov_b32 s8, 0x29a000
	s_nop 0
	v_addc_co_u32_e32 v45, vcc, 0, v35, vcc
	v_add_co_u32_e32 v46, vcc, s8, v34
	s_mov_b32 s8, 0x2ac000
	s_nop 0
	v_addc_co_u32_e32 v47, vcc, 0, v35, vcc
	v_add_co_u32_e32 v48, vcc, s8, v34
	s_mov_b32 s8, 0x2be000
	s_nop 0
	v_addc_co_u32_e32 v49, vcc, 0, v35, vcc
	v_add_co_u32_e32 v50, vcc, s8, v34
	s_mov_b32 s8, 0x480000
	s_nop 0
	v_addc_co_u32_e32 v51, vcc, 0, v35, vcc
	global_load_dword v91, v[36:37], off nt
	global_load_dword v92, v[38:39], off nt
	global_load_dword v93, v[40:41], off nt
	global_load_dword v94, v[42:43], off nt
	global_load_dword v95, v[44:45], off nt
	global_load_dword v96, v[46:47], off nt
	global_load_dword v97, v[48:49], off nt
	global_load_dword v98, v[50:51], off nt
	v_add_co_u32_e32 v36, vcc, s8, v34
	s_mov_b32 s8, 0x492000
	s_nop 0
	v_addc_co_u32_e32 v37, vcc, 0, v35, vcc
	v_add_co_u32_e32 v38, vcc, s8, v34
	s_mov_b32 s8, 0x4a4000
	s_nop 0
	v_addc_co_u32_e32 v39, vcc, 0, v35, vcc
	v_add_co_u32_e32 v40, vcc, s8, v34
	s_mov_b32 s8, 0x4b6000
	s_nop 0
	v_addc_co_u32_e32 v41, vcc, 0, v35, vcc
	v_add_co_u32_e32 v42, vcc, s8, v34
	s_mov_b32 s8, 0x4c8000
	s_nop 0
	v_addc_co_u32_e32 v43, vcc, 0, v35, vcc
	v_add_co_u32_e32 v44, vcc, s8, v34
	s_mov_b32 s8, 0x4da000
	s_nop 0
	v_addc_co_u32_e32 v45, vcc, 0, v35, vcc
	v_add_co_u32_e32 v46, vcc, s8, v34
	s_mov_b32 s8, 0x4ec000
	s_nop 0
	v_addc_co_u32_e32 v47, vcc, 0, v35, vcc
	v_add_co_u32_e32 v48, vcc, s8, v34
	s_mov_b32 s8, 0x4fe000
	s_nop 0
	v_addc_co_u32_e32 v49, vcc, 0, v35, vcc
	v_add_co_u32_e32 v50, vcc, s8, v34
	s_mov_b32 s8, 0x6c0000
	s_nop 0
	v_addc_co_u32_e32 v51, vcc, 0, v35, vcc
	global_load_dword v99, v[36:37], off nt
	global_load_dword v100, v[38:39], off nt
	global_load_dword v101, v[40:41], off nt
	global_load_dword v102, v[42:43], off nt
	global_load_dword v103, v[44:45], off nt
	global_load_dword v104, v[46:47], off nt
	global_load_dword v105, v[48:49], off nt
	global_load_dword v106, v[50:51], off nt
	v_add_co_u32_e32 v36, vcc, s8, v34
	s_mov_b32 s8, 0x6d2000
	s_nop 0
	v_addc_co_u32_e32 v37, vcc, 0, v35, vcc
	v_add_co_u32_e32 v38, vcc, s8, v34
	s_mov_b32 s8, 0x6e4000
	s_nop 0
	v_addc_co_u32_e32 v39, vcc, 0, v35, vcc
	v_add_co_u32_e32 v40, vcc, s8, v34
	s_mov_b32 s8, 0x6f6000
	s_nop 0
	v_addc_co_u32_e32 v41, vcc, 0, v35, vcc
	v_add_co_u32_e32 v42, vcc, s8, v34
	s_mov_b32 s8, 0x708000
	s_nop 0
	v_addc_co_u32_e32 v43, vcc, 0, v35, vcc
	v_add_co_u32_e32 v44, vcc, s8, v34
	s_mov_b32 s8, 0x71a000
	s_nop 0
	v_addc_co_u32_e32 v45, vcc, 0, v35, vcc
	v_add_co_u32_e32 v46, vcc, s8, v34
	s_mov_b32 s8, 0x72c000
	s_nop 0
	v_addc_co_u32_e32 v47, vcc, 0, v35, vcc
	v_add_co_u32_e32 v48, vcc, s8, v34
	s_mov_b32 s8, 0x73e000
	s_nop 0
	v_addc_co_u32_e32 v49, vcc, 0, v35, vcc
	v_add_co_u32_e32 v34, vcc, s8, v34
	v_lshl_add_u32 v90, v33, 1, 0
	s_nop 0
	v_addc_co_u32_e32 v35, vcc, 0, v35, vcc
	global_load_dword v115, v[36:37], off nt
	global_load_dword v116, v[38:39], off nt
	global_load_dword v117, v[40:41], off nt
	global_load_dword v118, v[42:43], off nt
	global_load_dword v119, v[44:45], off nt
	global_load_dword v120, v[46:47], off nt
	global_load_dword v121, v[48:49], off nt
	global_load_dword v122, v[34:35], off nt
	v_lshrrev_b32_e32 v35, 4, v128
	s_movk_i32 s10, 0x110
	v_mad_u32_u24 v33, v35, s10, v90
	v_lshrrev_b32_e32 v36, 4, v23
	s_waitcnt vmcnt(34)
	ds_write_b128 v33, v[12:15]
	v_mad_u32_u24 v12, v36, s10, v90
	v_lshrrev_b32_e32 v37, 4, v25
	s_waitcnt vmcnt(33)
	ds_write_b128 v12, v[8:11]
	v_mad_u32_u24 v8, v37, s10, v90
	v_lshrrev_b32_e32 v33, 4, v27
	s_waitcnt vmcnt(32)
	ds_write_b128 v8, v[16:19]
	s_and_saveexec_b64 s[8:9], s[4:5]
	v_mad_u32_u24 v8, v33, s10, v90
	ds_write_b128 v8, v[0:3]
	s_or_b64 exec, exec, s[8:9]
	v_lshrrev_b32_e32 v34, 4, v21
	s_and_saveexec_b64 s[8:9], s[6:7]
	v_mad_u32_u24 v8, v34, s10, v90
	ds_write_b128 v8, v[4:7]
	s_or_b64 exec, exec, s[8:9]
	v_mov_b32_e32 v21, 0
	v_mov_b32_e32 v23, v21
	v_mov_b32_e32 v25, v21
	v_mov_b32_e32 v27, v21
	v_lshl_add_u64 v[8:9], s[2:3], 0, v[22:23]
	v_lshl_add_u64 v[10:11], s[2:3], 0, v[24:25]
	v_lshl_add_u64 v[16:17], s[2:3], 0, v[26:27]
	v_lshl_add_u64 v[8:9], v[8:9], 0, v[20:21]
	v_lshl_add_u64 v[12:13], v[10:11], 0, v[20:21]
	v_lshl_add_u64 v[16:17], v[16:17], 0, v[20:21]
	global_load_dwordx4 v[8:11], v[8:9], off offset:256
	s_nop 0
	global_load_dwordx4 v[12:15], v[12:13], off offset:256
	s_nop 0
	global_load_dwordx4 v[16:19], v[16:17], off offset:256
	s_and_saveexec_b64 s[8:9], s[4:5]
	s_cbranch_execz .LBB0_221
	v_and_b32_e32 v0, 0xff000, v31
	v_mov_b32_e32 v1, v21
	v_lshl_add_u64 v[0:1], s[2:3], 0, v[0:1]
	v_lshl_add_u64 v[0:1], v[0:1], 0, v[20:21]
	global_load_dwordx4 v[0:3], v[0:1], off offset:256

.LBB0_223:
	s_or_b64 exec, exec, s[8:9]
	v_lshlrev_b64 v[20:21], 2, v[56:57]
	v_lshl_add_u64 v[22:23], v[28:29], 0, v[20:21]
	v_add_co_u32_e32 v24, vcc, 0x900000, v22
	v_mul_u32_u24_e32 v32, 0x110, v36
	s_nop 0
	v_addc_co_u32_e32 v25, vcc, 0, v23, vcc
	v_add_co_u32_e32 v26, vcc, 0x912000, v22
	v_mul_u32_u24_e32 v31, 0x110, v35
	s_nop 0
	v_addc_co_u32_e32 v27, vcc, 0, v23, vcc
	v_add_co_u32_e32 v28, vcc, 0x924000, v22
	v_mul_u32_u24_e32 v35, 0x110, v37
	s_nop 0
	v_addc_co_u32_e32 v29, vcc, 0, v23, vcc
	v_add_co_u32_e32 v36, vcc, 0x936000, v22
	v_mov_b32_e32 v59, 0
	s_nop 0
	v_addc_co_u32_e32 v37, vcc, 0, v23, vcc
	v_add_co_u32_e32 v38, vcc, 0x948000, v22
	v_mov_b32_e32 v129, v59
	s_nop 0
	v_addc_co_u32_e32 v39, vcc, 0, v23, vcc
	v_add_co_u32_e32 v40, vcc, 0x95a000, v22
	s_mov_b64 s[2:3], 0x80000
	s_nop 0
	v_addc_co_u32_e32 v41, vcc, 0, v23, vcc
	v_add_co_u32_e32 v42, vcc, 0x96c000, v22
	s_mov_b32 s27, 0
	s_nop 0
	v_addc_co_u32_e32 v43, vcc, 0, v23, vcc
	v_add_co_u32_e32 v44, vcc, 0x97e000, v22
	v_mul_u32_u24_e32 v124, 0x110, v33
	s_nop 0
	v_addc_co_u32_e32 v45, vcc, 0, v23, vcc
	global_load_dword v107, v[24:25], off nt
	global_load_dword v108, v[26:27], off nt
	global_load_dword v109, v[28:29], off nt
	global_load_dword v110, v[36:37], off nt
	global_load_dword v111, v[38:39], off nt
	global_load_dword v112, v[40:41], off nt
	global_load_dword v113, v[42:43], off nt
	global_load_dword v114, v[44:45], off nt
	v_add_co_u32_e32 v24, vcc, 0xb40000, v22
	v_mul_u32_u24_e32 v125, 0x110, v34
	s_nop 0
	v_addc_co_u32_e32 v25, vcc, 0, v23, vcc
	v_add_co_u32_e32 v26, vcc, 0xb52000, v22
	v_lshlrev_b32_e32 v58, 4, v30
	s_nop 0
	v_addc_co_u32_e32 v27, vcc, 0, v23, vcc
	v_add_co_u32_e32 v28, vcc, 0xb64000, v22
	s_mov_b64 s[8:9], 0x1200000
	s_nop 0
	v_addc_co_u32_e32 v29, vcc, 0, v23, vcc
	v_add_co_u32_e32 v36, vcc, 0xb76000, v22
	v_add_u32_e32 v133, v90, v32
	s_nop 0
	v_addc_co_u32_e32 v37, vcc, 0, v23, vcc
	v_add_co_u32_e32 v38, vcc, 0xb88000, v22
	v_add_u32_e32 v134, v90, v35
	s_nop 0
	v_addc_co_u32_e32 v39, vcc, 0, v23, vcc
	v_add_co_u32_e32 v40, vcc, 0xb9a000, v22
	v_mov_b32_e32 v32, v59
	s_nop 0
	v_addc_co_u32_e32 v41, vcc, 0, v23, vcc
	v_add_co_u32_e32 v42, vcc, 0xbac000, v22
	v_mov_b32_e32 v33, v59
	s_nop 0
	v_addc_co_u32_e32 v43, vcc, 0, v23, vcc
	v_add_co_u32_e32 v44, vcc, 0xbbe000, v22
	v_mov_b32_e32 v34, v59
	s_nop 0
	v_addc_co_u32_e32 v45, vcc, 0, v23, vcc
	global_load_dword v126, v[24:25], off nt
	global_load_dword v127, v[26:27], off nt
	global_load_dword v130, v[28:29], off nt
	global_load_dword v131, v[36:37], off nt
	global_load_dword v132, v[38:39], off nt
	global_load_dword v135, v[40:41], off nt
	global_load_dword v136, v[42:43], off nt
	global_load_dword v137, v[44:45], off nt
	v_add_co_u32_e32 v24, vcc, 0xd80000, v22
	v_mov_b32_e32 v35, v59
	s_nop 0
	v_addc_co_u32_e32 v25, vcc, 0, v23, vcc
	v_add_co_u32_e32 v26, vcc, 0xd92000, v22
	v_mov_b32_e32 v46, v59
	s_nop 0
	v_addc_co_u32_e32 v27, vcc, 0, v23, vcc
	v_add_co_u32_e32 v28, vcc, 0xda4000, v22
	v_mov_b32_e32 v47, v59
	s_nop 0
	v_addc_co_u32_e32 v29, vcc, 0, v23, vcc
	v_add_co_u32_e32 v36, vcc, 0xdb6000, v22
	v_mov_b32_e32 v48, v59
	s_nop 0
	v_addc_co_u32_e32 v37, vcc, 0, v23, vcc
	v_add_co_u32_e32 v38, vcc, 0xdc8000, v22
	v_mov_b32_e32 v49, v59
	s_nop 0
	v_addc_co_u32_e32 v39, vcc, 0, v23, vcc
	v_add_co_u32_e32 v40, vcc, 0xdda000, v22
	v_mov_b32_e32 v50, v59
	s_nop 0
	v_addc_co_u32_e32 v41, vcc, 0, v23, vcc
	v_add_co_u32_e32 v42, vcc, 0xdec000, v22
	v_mov_b32_e32 v51, v59
	s_nop 0
	v_addc_co_u32_e32 v43, vcc, 0, v23, vcc
	v_add_co_u32_e32 v44, vcc, 0xdfe000, v22
	v_mov_b32_e32 v52, v59
	s_nop 0
	v_addc_co_u32_e32 v45, vcc, 0, v23, vcc
	global_load_dword v138, v[24:25], off nt
	global_load_dword v139, v[26:27], off nt
	global_load_dword v140, v[28:29], off nt
	global_load_dword v142, v[36:37], off nt
	global_load_dword v143, v[38:39], off nt
	global_load_dword v144, v[40:41], off nt
	global_load_dword v145, v[42:43], off nt
	global_load_dword v146, v[44:45], off nt
	v_add_co_u32_e32 v24, vcc, 0xfc0000, v22
	v_mov_b32_e32 v44, v59
	s_nop 0
	v_addc_co_u32_e32 v25, vcc, 0, v23, vcc
	v_add_co_u32_e32 v26, vcc, 0xfd2000, v22
	v_mov_b32_e32 v45, v59
	s_nop 0
	v_addc_co_u32_e32 v27, vcc, 0, v23, vcc
	v_add_co_u32_e32 v28, vcc, 0xfe4000, v22
	v_mov_b32_e32 v53, v59
	s_nop 0
	v_addc_co_u32_e32 v29, vcc, 0, v23, vcc
	v_add_co_u32_e32 v36, vcc, 0xff6000, v22
	v_mov_b32_e32 v54, v59
	s_nop 0
	v_addc_co_u32_e32 v37, vcc, 0, v23, vcc
	v_add_co_u32_e32 v38, vcc, 0x1008000, v22
	v_mov_b32_e32 v55, v59
	s_nop 0
	v_addc_co_u32_e32 v39, vcc, 0, v23, vcc
	v_add_co_u32_e32 v40, vcc, 0x101a000, v22
	s_nop 1
	v_addc_co_u32_e32 v41, vcc, 0, v23, vcc
	v_add_co_u32_e32 v42, vcc, 0x102c000, v22
	s_nop 1
	v_addc_co_u32_e32 v43, vcc, 0, v23, vcc
	v_add_co_u32_e32 v22, vcc, 0x103e000, v22
	s_nop 1
	v_addc_co_u32_e32 v23, vcc, 0, v23, vcc
	global_load_dword v147, v[24:25], off nt
	global_load_dword v148, v[26:27], off nt
	global_load_dword v149, v[28:29], off nt
	global_load_dword v150, v[36:37], off nt
	global_load_dword v151, v[38:39], off nt
	global_load_dword v152, v[40:41], off nt
	global_load_dword v153, v[42:43], off nt
	global_load_dword v154, v[22:23], off nt
	v_mul_u32_u24_e32 v22, 0x110, v30
	v_lshlrev_b32_e32 v23, 4, v79
	v_add3_u32 v123, 0, v22, v23
	v_lshlrev_b64 v[22:23], 8, v[128:129]
	v_lshl_add_u64 v[24:25], v[22:23], 0, s[2:3]
	v_and_b32_e32 v25, 0x1ff, v25
	v_and_b32_e32 v24, 0xfffff000, v24
	s_mov_b64 s[2:3], 0x60000
	v_lshl_add_u64 v[60:61], s[50:51], 0, v[24:25]
	v_lshl_add_u64 v[24:25], v[22:23], 0, s[2:3]
	v_and_b32_e32 v25, 0x1ff, v25
	v_and_b32_e32 v24, 0xfffff000, v24
	s_mov_b64 s[2:3], 0x40000
	v_lshl_add_u64 v[62:63], s[50:51], 0, v[24:25]
	v_lshl_add_u64 v[24:25], v[22:23], 0, s[2:3]
	v_and_b32_e32 v25, 0x1ff, v25
	v_and_b32_e32 v24, 0xfffff000, v24
	s_mov_b64 s[2:3], 0x20000
	v_lshl_add_u64 v[64:65], s[50:51], 0, v[24:25]
	v_lshl_add_u64 v[24:25], v[22:23], 0, s[2:3]
	s_mov_b32 s2, 0x90000
	v_mad_u64_u32 v[20:21], s[2:3], v79, s2, v[20:21]
	v_and_b32_e32 v25, 0x1ff, v25
	v_and_b32_e32 v24, 0xfffff000, v24
	v_and_b32_e32 v22, 0xfffff000, v22
	v_lshl_add_u64 v[20:21], s[30:31], 0, v[20:21]
	s_mov_b64 s[2:3], 0x223e000
	v_lshl_add_u64 v[66:67], s[50:51], 0, v[24:25]
	v_lshl_add_u64 v[68:69], s[50:51], 0, v[22:23]
	v_lshl_add_u64 v[70:71], v[20:21], 0, s[2:3]
	s_mov_b64 s[2:3], 0x200
	v_add_u32_e32 v129, v90, v31
	v_mov_b32_e32 v20, v59
	v_mov_b32_e32 v21, v59
	v_mov_b32_e32 v22, v59
	v_mov_b32_e32 v23, v59
	v_mov_b32_e32 v24, v59
	v_mov_b32_e32 v25, v59
	v_mov_b32_e32 v26, v59
	v_mov_b32_e32 v27, v59
	v_mov_b32_e32 v28, v59
	v_mov_b32_e32 v29, v59
	v_mov_b32_e32 v30, v59
	v_mov_b32_e32 v31, v59
	v_mov_b32_e32 v36, v59
	v_mov_b32_e32 v37, v59
	v_mov_b32_e32 v38, v59
	v_mov_b32_e32 v39, v59
	v_mov_b32_e32 v40, v59
	v_mov_b32_e32 v41, v59
	v_mov_b32_e32 v42, v59
	v_mov_b32_e32 v43, v59
	v_add_u32_e32 v141, 0x9900, v123
	s_waitcnt lgkmcnt(0)
	s_barrier
	s_branch .LBB0_226
.LBB0_224:
	s_or_b64 exec, exec, s[12:13]
	v_add_co_u32_e32 v72, vcc, 0xff8c2000, v70
	s_nop 1
	v_addc_co_u32_e32 v73, vcc, -1, v71, vcc
	v_add_co_u32_e32 v74, vcc, 0xff8d4000, v70
	s_nop 1
	v_addc_co_u32_e32 v75, vcc, -1, v71, vcc
	v_add_co_u32_e32 v76, vcc, 0xff8e6000, v70
	s_nop 1
	v_addc_co_u32_e32 v77, vcc, -1, v71, vcc
	v_add_co_u32_e32 v110, vcc, 0xff8f8000, v70
	s_nop 1
	v_addc_co_u32_e32 v111, vcc, -1, v71, vcc
	v_add_co_u32_e32 v112, vcc, 0xff90a000, v70
	s_nop 1
	v_addc_co_u32_e32 v113, vcc, -1, v71, vcc
	v_add_co_u32_e32 v126, vcc, 0xff91c000, v70
	s_nop 1
	v_addc_co_u32_e32 v127, vcc, -1, v71, vcc
	v_add_co_u32_e32 v130, vcc, 0xff92e000, v70
	s_nop 1
	v_addc_co_u32_e32 v131, vcc, -1, v71, vcc
	v_add_co_u32_e32 v136, vcc, 0xff940000, v70
	s_nop 1
	v_addc_co_u32_e32 v137, vcc, -1, v71, vcc
	global_load_dword v107, v[72:73], off nt
	global_load_dword v108, v[74:75], off nt
	global_load_dword v109, v[76:77], off nt
	s_nop 0
	global_load_dword v110, v[110:111], off nt
	s_nop 0
	global_load_dword v111, v[112:113], off nt
	s_nop 0
	global_load_dword v112, v[126:127], off nt
	global_load_dword v113, v[130:131], off nt
	global_load_dword v114, v[136:137], off nt
	v_add_co_u32_e32 v72, vcc, 0xffb02000, v70
	s_nop 1
	v_addc_co_u32_e32 v73, vcc, -1, v71, vcc
	v_add_co_u32_e32 v74, vcc, 0xffb14000, v70
	s_nop 1
	v_addc_co_u32_e32 v75, vcc, -1, v71, vcc
	v_add_co_u32_e32 v76, vcc, 0xffb26000, v70
	s_nop 1
	v_addc_co_u32_e32 v77, vcc, -1, v71, vcc
	v_add_co_u32_e32 v136, vcc, 0xffb38000, v70
	s_nop 1
	v_addc_co_u32_e32 v137, vcc, -1, v71, vcc
	v_add_co_u32_e32 v138, vcc, 0xffb4a000, v70
	s_nop 1
	v_addc_co_u32_e32 v139, vcc, -1, v71, vcc
	v_add_co_u32_e32 v142, vcc, 0xffb5c000, v70
	s_nop 1
	v_addc_co_u32_e32 v143, vcc, -1, v71, vcc
	v_add_co_u32_e32 v144, vcc, 0xffb6e000, v70
	s_nop 1
	v_addc_co_u32_e32 v145, vcc, -1, v71, vcc
	v_add_co_u32_e32 v146, vcc, 0xffb80000, v70
	s_nop 1
	v_addc_co_u32_e32 v147, vcc, -1, v71, vcc
	global_load_dword v126, v[72:73], off nt
	global_load_dword v127, v[74:75], off nt
	global_load_dword v130, v[76:77], off nt
	global_load_dword v131, v[136:137], off nt
	global_load_dword v132, v[138:139], off nt
	global_load_dword v135, v[142:143], off nt
	s_nop 0
	global_load_dword v136, v[144:145], off nt
	global_load_dword v137, v[146:147], off nt
	v_add_co_u32_e32 v72, vcc, 0xffd42000, v70
	s_nop 1
	v_addc_co_u32_e32 v73, vcc, -1, v71, vcc
	v_add_co_u32_e32 v74, vcc, 0xffd54000, v70
	s_nop 1
	v_addc_co_u32_e32 v75, vcc, -1, v71, vcc
	v_add_co_u32_e32 v76, vcc, 0xffd66000, v70
	s_nop 1
	v_addc_co_u32_e32 v77, vcc, -1, v71, vcc
	v_add_co_u32_e32 v142, vcc, 0xffd78000, v70
	s_nop 1
	v_addc_co_u32_e32 v143, vcc, -1, v71, vcc
	v_add_co_u32_e32 v144, vcc, 0xffd8a000, v70
	s_nop 1
	v_addc_co_u32_e32 v145, vcc, -1, v71, vcc
	v_add_co_u32_e32 v146, vcc, 0xffd9c000, v70
	s_nop 1
	v_addc_co_u32_e32 v147, vcc, -1, v71, vcc
	v_add_co_u32_e32 v148, vcc, 0xffdae000, v70
	s_nop 1
	v_addc_co_u32_e32 v149, vcc, -1, v71, vcc
	v_add_co_u32_e32 v150, vcc, 0xffdc0000, v70
	s_nop 1
	v_addc_co_u32_e32 v151, vcc, -1, v71, vcc
	global_load_dword v138, v[72:73], off nt
	global_load_dword v139, v[74:75], off nt
	global_load_dword v140, v[76:77], off nt
	s_nop 0
	global_load_dword v142, v[142:143], off nt
	s_nop 0
	global_load_dword v143, v[144:145], off nt
	s_nop 0
	global_load_dword v144, v[146:147], off nt
	global_load_dword v145, v[148:149], off nt
	s_nop 0
	global_load_dword v146, v[150:151], off nt
	v_add_co_u32_e32 v72, vcc, 0xfff82000, v70
	s_nop 1
	v_addc_co_u32_e32 v73, vcc, -1, v71, vcc
	v_add_co_u32_e32 v74, vcc, 0xfff94000, v70
	s_nop 1
	v_addc_co_u32_e32 v75, vcc, -1, v71, vcc
	v_add_co_u32_e32 v76, vcc, 0xfffa6000, v70
	s_nop 1
	v_addc_co_u32_e32 v77, vcc, -1, v71, vcc
	v_add_co_u32_e32 v150, vcc, 0xfffb8000, v70
	s_nop 1
	v_addc_co_u32_e32 v151, vcc, -1, v71, vcc
	v_add_co_u32_e32 v152, vcc, 0xfffca000, v70
	s_nop 1
	v_addc_co_u32_e32 v153, vcc, -1, v71, vcc
	v_add_co_u32_e32 v154, vcc, 0xfffdc000, v70
	s_nop 1
	v_addc_co_u32_e32 v155, vcc, -1, v71, vcc
	v_add_co_u32_e32 v156, vcc, 0xfffee000, v70
	s_nop 1
	v_addc_co_u32_e32 v157, vcc, -1, v71, vcc
	global_load_dword v147, v[72:73], off nt
	global_load_dword v148, v[74:75], off nt
	global_load_dword v149, v[76:77], off nt
	s_nop 0
	global_load_dword v150, v[150:151], off nt
	s_nop 0
	global_load_dword v151, v[152:153], off nt
	s_nop 0
	global_load_dword v152, v[154:155], off nt
	global_load_dword v153, v[156:157], off nt
	s_nop 0
	global_load_dword v154, v[70:71], off nt

.LBB0_235:
	s_or_b64 exec, exec, s[14:15]
	v_add_co_u32_e32 v82, vcc, 0xfefc2000, v70
	s_nop 1
	v_addc_co_u32_e32 v83, vcc, -1, v71, vcc
	v_add_co_u32_e32 v84, vcc, 0xfefd4000, v70
	s_nop 1
	v_addc_co_u32_e32 v85, vcc, -1, v71, vcc
	v_add_co_u32_e32 v86, vcc, 0xfefe6000, v70
	s_nop 1
	v_addc_co_u32_e32 v87, vcc, -1, v71, vcc
	v_add_co_u32_e32 v88, vcc, 0xfeff8000, v70
	s_nop 1
	v_addc_co_u32_e32 v89, vcc, -1, v71, vcc
	v_add_co_u32_e32 v92, vcc, 0xff00a000, v70
	s_nop 1
	v_addc_co_u32_e32 v93, vcc, -1, v71, vcc
	v_add_co_u32_e32 v94, vcc, 0xff01c000, v70
	s_nop 1
	v_addc_co_u32_e32 v95, vcc, -1, v71, vcc
	v_add_co_u32_e32 v96, vcc, 0xff02e000, v70
	s_nop 1
	v_addc_co_u32_e32 v97, vcc, -1, v71, vcc
	v_add_co_u32_e32 v98, vcc, 0xff040000, v70
	s_nop 1
	v_addc_co_u32_e32 v99, vcc, -1, v71, vcc
	global_load_dword v82, v[82:83], off nt
	s_nop 0
	global_load_dword v83, v[84:85], off nt
	s_nop 0
	global_load_dword v84, v[86:87], off nt
	global_load_dword v85, v[88:89], off nt
	s_nop 0
	global_load_dword v86, v[92:93], off nt
	global_load_dword v87, v[94:95], off nt
	global_load_dword v88, v[96:97], off nt
	global_load_dword v89, v[98:99], off nt
	v_add_co_u32_e32 v92, vcc, 0xff202000, v70
	s_nop 1
	v_addc_co_u32_e32 v93, vcc, -1, v71, vcc
	v_add_co_u32_e32 v94, vcc, 0xff214000, v70
	s_nop 1
	v_addc_co_u32_e32 v95, vcc, -1, v71, vcc
	v_add_co_u32_e32 v96, vcc, 0xff226000, v70
	s_nop 1
	v_addc_co_u32_e32 v97, vcc, -1, v71, vcc
	v_add_co_u32_e32 v98, vcc, 0xff238000, v70
	s_nop 1
	v_addc_co_u32_e32 v99, vcc, -1, v71, vcc
	v_add_co_u32_e32 v100, vcc, 0xff24a000, v70
	s_nop 1
	v_addc_co_u32_e32 v101, vcc, -1, v71, vcc
	v_add_co_u32_e32 v102, vcc, 0xff25c000, v70
	s_nop 1
	v_addc_co_u32_e32 v103, vcc, -1, v71, vcc
	v_add_co_u32_e32 v104, vcc, 0xff26e000, v70
	s_nop 1
	v_addc_co_u32_e32 v105, vcc, -1, v71, vcc
	v_add_co_u32_e32 v116, vcc, 0xff280000, v70
	s_nop 1
	v_addc_co_u32_e32 v117, vcc, -1, v71, vcc
	global_load_dword v91, v[92:93], off nt
	s_nop 0
	global_load_dword v92, v[94:95], off nt
	global_load_dword v93, v[96:97], off nt
	s_nop 0
	global_load_dword v94, v[98:99], off nt
	global_load_dword v95, v[100:101], off nt
	global_load_dword v96, v[102:103], off nt
	global_load_dword v97, v[104:105], off nt
	s_nop 0
	global_load_dword v98, v[116:117], off nt
	v_add_co_u32_e32 v100, vcc, 0xff442000, v70
	s_nop 1
	v_addc_co_u32_e32 v101, vcc, -1, v71, vcc
	v_add_co_u32_e32 v102, vcc, 0xff454000, v70
	s_nop 1
	v_addc_co_u32_e32 v103, vcc, -1, v71, vcc
	v_add_co_u32_e32 v104, vcc, 0xff466000, v70
	s_nop 1
	v_addc_co_u32_e32 v105, vcc, -1, v71, vcc
	v_add_co_u32_e32 v116, vcc, 0xff478000, v70
	s_nop 1
	v_addc_co_u32_e32 v117, vcc, -1, v71, vcc
	v_add_co_u32_e32 v118, vcc, 0xff48a000, v70
	s_nop 1
	v_addc_co_u32_e32 v119, vcc, -1, v71, vcc
	v_add_co_u32_e32 v120, vcc, 0xff49c000, v70
	s_nop 1
	v_addc_co_u32_e32 v121, vcc, -1, v71, vcc
	v_add_co_u32_e32 v156, vcc, 0xff4ae000, v70
	s_nop 1
	v_addc_co_u32_e32 v157, vcc, -1, v71, vcc
	v_add_co_u32_e32 v158, vcc, 0xff4c0000, v70
	s_nop 1
	v_addc_co_u32_e32 v159, vcc, -1, v71, vcc
	global_load_dword v99, v[100:101], off nt
	s_nop 0
	global_load_dword v100, v[102:103], off nt
	global_load_dword v101, v[104:105], off nt
	s_nop 0
	global_load_dword v102, v[116:117], off nt
	global_load_dword v103, v[118:119], off nt
	global_load_dword v104, v[120:121], off nt
	global_load_dword v105, v[156:157], off nt
	global_load_dword v106, v[158:159], off nt
	v_add_co_u32_e32 v116, vcc, 0xff682000, v70
	s_nop 1
	v_addc_co_u32_e32 v117, vcc, -1, v71, vcc
	v_add_co_u32_e32 v118, vcc, 0xff694000, v70
	s_nop 1
	v_addc_co_u32_e32 v119, vcc, -1, v71, vcc
	v_add_co_u32_e32 v120, vcc, 0xff6a6000, v70
	s_nop 1
	v_addc_co_u32_e32 v121, vcc, -1, v71, vcc
	v_add_co_u32_e32 v156, vcc, 0xff6b8000, v70
	s_nop 1
	v_addc_co_u32_e32 v157, vcc, -1, v71, vcc
	v_add_co_u32_e32 v158, vcc, 0xff6ca000, v70
	s_nop 1
	v_addc_co_u32_e32 v159, vcc, -1, v71, vcc
	v_add_co_u32_e32 v160, vcc, 0xff6dc000, v70
	s_nop 1
	v_addc_co_u32_e32 v161, vcc, -1, v71, vcc
	v_add_co_u32_e32 v162, vcc, 0xff6ee000, v70
	s_nop 1
	v_addc_co_u32_e32 v163, vcc, -1, v71, vcc
	v_add_co_u32_e32 v164, vcc, 0xff700000, v70
	s_nop 1
	v_addc_co_u32_e32 v165, vcc, -1, v71, vcc
	global_load_dword v115, v[116:117], off nt
	s_nop 0
	global_load_dword v116, v[118:119], off nt
	global_load_dword v117, v[120:121], off nt
	s_nop 0
	global_load_dword v118, v[156:157], off nt
	global_load_dword v119, v[158:159], off nt
	global_load_dword v120, v[160:161], off nt
	global_load_dword v121, v[162:163], off nt
	global_load_dword v122, v[164:165], off nt

.LBB0_247:
	v_readlane_b32 s52, v235, 1
	v_readlane_b32 s53, v235, 2
	s_waitcnt vmcnt(32)
	v_ashrrev_i32_e32 v4, 11, v81
	v_mov_b32_e32 v0, s52
	v_mov_b32_e32 v1, s53
	v_lshl_add_u64 v[0:1], v[56:57], 2, v[0:1]
	global_load_dword v2, v[0:1], off nt
	s_mov_b32 s2, 0x55555556
	v_mul_hi_i32 v0, v4, s2
	v_lshrrev_b32_e32 v1, 31, v0
	v_add_u32_e32 v0, v0, v1
	v_mad_i32_i24 v5, v0, -3, v4
	v_and_b32_e32 v1, 0x7ff, v56
	v_cmp_lt_i32_e32 vcc, 1, v5
	v_readlane_b32 s54, v235, 3
	v_readlane_b32 s55, v235, 4
	v_readlane_b32 s56, v235, 5
	v_readlane_b32 s57, v235, 6
	v_readlane_b32 s58, v235, 7
	v_readlane_b32 s59, v235, 8
	v_readlane_b32 s60, v235, 9
	v_readlane_b32 s61, v235, 10
	v_readlane_b32 s62, v235, 11
	v_readlane_b32 s63, v235, 12
	v_readlane_b32 s64, v235, 13
	v_readlane_b32 s65, v235, 14
	v_readlane_b32 s66, v235, 15
	v_readlane_b32 s67, v235, 16
	s_and_saveexec_b64 s[2:3], vcc
	s_xor_b64 s[2:3], exec, s[2:3]
	s_cbranch_execz .LBB0_251
	v_cmp_eq_u32_e32 vcc, 2, v5
	v_mov_b32_e32 v3, 1.0
	s_and_saveexec_b64 s[4:5], vcc
	s_cbranch_execz .LBB0_250
	v_readlane_b32 s52, v235, 1
	v_readlane_b32 s56, v235, 5
	v_readlane_b32 s57, v235, 6
	v_lshl_or_b32 v0, v0, 11, v1
	v_mov_b32_e32 v6, s56
	v_mov_b32_e32 v7, s57
	v_ashrrev_i32_e32 v1, 31, v0
	v_lshl_add_u64 v[0:1], v[0:1], 2, v[6:7]
	global_load_dword v0, v[0:1], off nt
	v_add_u32_e32 v1, -3, v4
	v_cmp_gt_u32_e32 vcc, 3, v1
	v_readlane_b32 s53, v235, 2
	v_readlane_b32 s54, v235, 3
	v_cndmask_b32_e64 v1, 0.5, 1.0, vcc
	v_readlane_b32 s55, v235, 4
	v_readlane_b32 s58, v235, 7
	v_readlane_b32 s59, v235, 8
	v_readlane_b32 s60, v235, 9
	v_readlane_b32 s61, v235, 10
	v_readlane_b32 s62, v235, 11
	v_readlane_b32 s63, v235, 12
	v_readlane_b32 s64, v235, 13
	v_readlane_b32 s65, v235, 14
	v_readlane_b32 s66, v235, 15
	v_readlane_b32 s67, v235, 16
	s_waitcnt vmcnt(0)
	v_mul_f32_e32 v3, v1, v0

.LBB0_251:
	s_andn2_saveexec_b64 s[2:3], s[2:3]
	s_cbranch_execz .LBB0_255
	v_cmp_eq_u32_e32 vcc, 1, v5
	v_mov_b32_e32 v3, 1.0
	s_and_saveexec_b64 s[4:5], vcc
	s_cbranch_execz .LBB0_254
	v_readlane_b32 s52, v235, 1
	v_readlane_b32 s54, v235, 3
	v_readlane_b32 s55, v235, 4
	v_lshl_or_b32 v0, v0, 11, v1
	v_mov_b32_e32 v4, s54
	v_mov_b32_e32 v5, s55
	v_ashrrev_i32_e32 v1, 31, v0
	v_lshl_add_u64 v[0:1], v[0:1], 2, v[4:5]
	global_load_dword v3, v[0:1], off nt
	s_waitcnt vmcnt(1)
	v_add_f32_e32 v2, 1.0, v2
	v_readlane_b32 s53, v235, 2
	v_readlane_b32 s56, v235, 5
	v_readlane_b32 s57, v235, 6
	v_readlane_b32 s58, v235, 7
	v_readlane_b32 s59, v235, 8
	v_readlane_b32 s60, v235, 9
	v_readlane_b32 s61, v235, 10
	v_readlane_b32 s62, v235, 11
	v_readlane_b32 s63, v235, 12
	v_readlane_b32 s64, v235, 13
	v_readlane_b32 s65, v235, 14
	v_readlane_b32 s66, v235, 15
	v_readlane_b32 s67, v235, 16

.LBB0_737:
	s_or_b64 exec, exec, s[4:5]
	v_lshrrev_b32_e32 v32, 3, v134
	v_lshlrev_b32_e32 v134, 2, v132
	v_lshl_add_u64 v[2:3], v[0:1], 0, v[134:135]
	v_lshlrev_b32_e32 v162, 2, v142
	v_mov_b32_e32 v163, v135
	global_load_dwordx4 v[24:27], v[2:3], off
	global_load_dwordx4 v[20:23], v[2:3], off offset:1024
	global_load_dwordx4 v[16:19], v[2:3], off offset:2048
	global_load_dwordx4 v[12:15], v[2:3], off offset:3072
	v_lshl_add_u64 v[2:3], v[0:1], 0, v[162:163]
	v_lshlrev_b32_e32 v160, 2, v144
	v_mov_b32_e32 v161, v135
	v_lshlrev_b32_e32 v158, 2, v146
	v_mov_b32_e32 v159, v135
	v_lshlrev_b32_e32 v156, 2, v148
	v_mov_b32_e32 v157, v135
	v_lshl_add_u64 v[4:5], v[0:1], 0, v[160:161]
	global_load_dwordx4 v[28:31], v[2:3], off
	global_load_dwordx4 v[8:11], v[4:5], off
	v_lshl_add_u64 v[2:3], v[0:1], 0, v[158:159]
	v_lshl_add_u64 v[0:1], v[0:1], 0, v[156:157]
	global_load_dwordx4 v[4:7], v[2:3], off
	s_nop 0
	global_load_dwordx4 v[0:3], v[0:1], off
	v_ashrrev_i32_e32 v33, 12, v130
	v_add_u32_e32 v32, 2, v32
	v_cndmask_b32_e32 v34, v32, v33, vcc
	v_mov_b64_e32 v[32:33], s[8:9]
	v_mad_i64_i32 v[64:65], s[4:5], v34, s58, v[32:33]
	v_lshlrev_b64 v[56:57], 11, v[154:155]
	v_or_b32_e32 v32, v56, v132
	v_mov_b32_e32 v33, v57
	v_lshlrev_b64 v[32:33], 1, v[32:33]
	v_lshl_add_u64 v[34:35], s[10:11], 0, v[32:33]
	v_lshl_add_u64 v[36:37], s[14:15], 0, v[32:33]
	v_lshl_add_u64 v[38:39], s[12:13], 0, v[32:33]
	v_lshl_add_u64 v[32:33], s[26:27], 0, v[32:33]
	global_load_dwordx2 v[100:101], v[34:35], off nt
	global_load_dwordx2 v[102:103], v[36:37], off nt
	global_load_dwordx2 v[104:105], v[38:39], off nt
	global_load_dwordx2 v[106:107], v[32:33], off nt
	v_or_b32_e32 v34, v56, v136
	v_mov_b32_e32 v35, v57
	v_lshl_add_u64 v[58:59], v[64:65], 0, s[52:53]
	v_lshlrev_b64 v[36:37], 1, v[34:35]
	v_lshl_add_u64 v[32:33], v[58:59], 0, v[134:135]
	v_lshl_add_u64 v[38:39], s[10:11], 0, v[36:37]
	global_load_dwordx4 v[32:35], v[32:33], off
	s_nop 0
	global_load_dwordx2 v[108:109], v[38:39], off nt
	v_lshl_add_u64 v[38:39], s[14:15], 0, v[36:37]
	v_lshl_add_u64 v[40:41], s[12:13], 0, v[36:37]
	v_lshl_add_u64 v[36:37], s[26:27], 0, v[36:37]
	global_load_dwordx2 v[110:111], v[38:39], off nt
	global_load_dwordx2 v[112:113], v[40:41], off nt
	global_load_dwordx2 v[114:115], v[36:37], off nt
	v_or_b32_e32 v38, v56, v138
	v_mov_b32_e32 v39, v57
	v_lshlrev_b32_e32 v66, 2, v136
	v_mov_b32_e32 v67, v135
	v_lshlrev_b64 v[40:41], 1, v[38:39]
	v_lshl_add_u64 v[36:37], v[58:59], 0, v[66:67]
	v_lshl_add_u64 v[42:43], s[10:11], 0, v[40:41]
	global_load_dwordx4 v[36:39], v[36:37], off
	s_nop 0
	global_load_dwordx2 v[116:117], v[42:43], off nt
	v_lshl_add_u64 v[42:43], s[14:15], 0, v[40:41]
	v_lshl_add_u64 v[44:45], s[12:13], 0, v[40:41]
	v_lshl_add_u64 v[40:41], s[26:27], 0, v[40:41]
	global_load_dwordx2 v[118:119], v[42:43], off nt
	global_load_dwordx2 v[120:121], v[44:45], off nt
	global_load_dwordx2 v[122:123], v[40:41], off nt
	v_or_b32_e32 v42, v56, v140
	v_mov_b32_e32 v43, v57
	v_lshlrev_b32_e32 v68, 2, v138
	v_mov_b32_e32 v69, v135
	v_lshlrev_b64 v[44:45], 1, v[42:43]
	v_lshl_add_u64 v[40:41], v[58:59], 0, v[68:69]
	v_lshl_add_u64 v[46:47], s[10:11], 0, v[44:45]
	global_load_dwordx4 v[40:43], v[40:41], off
	s_nop 0
	global_load_dwordx2 v[124:125], v[46:47], off nt
	v_lshl_add_u64 v[46:47], s[14:15], 0, v[44:45]
	v_lshl_add_u64 v[48:49], s[12:13], 0, v[44:45]
	v_lshl_add_u64 v[44:45], s[26:27], 0, v[44:45]
	global_load_dwordx2 v[126:127], v[46:47], off nt
	global_load_dwordx2 v[180:181], v[48:49], off nt
	global_load_dwordx2 v[182:183], v[44:45], off nt
	v_or_b32_e32 v46, v56, v142
	v_mov_b32_e32 v47, v57
	v_lshlrev_b32_e32 v70, 2, v140
	v_mov_b32_e32 v71, v135
	v_lshlrev_b64 v[48:49], 1, v[46:47]
	v_lshl_add_u64 v[44:45], v[58:59], 0, v[70:71]
	v_lshl_add_u64 v[50:51], s[10:11], 0, v[48:49]
	global_load_dwordx4 v[44:47], v[44:45], off
	s_nop 0
	global_load_dwordx2 v[184:185], v[50:51], off nt
	v_lshl_add_u64 v[50:51], s[14:15], 0, v[48:49]
	v_lshl_add_u64 v[52:53], s[12:13], 0, v[48:49]
	v_lshl_add_u64 v[48:49], s[26:27], 0, v[48:49]
	global_load_dwordx2 v[186:187], v[50:51], off nt
	global_load_dwordx2 v[98:99], v[52:53], off nt
	global_load_dwordx2 v[96:97], v[48:49], off nt
	v_or_b32_e32 v50, v56, v144
	v_mov_b32_e32 v51, v57
	v_lshlrev_b64 v[52:53], 1, v[50:51]
	v_lshl_add_u64 v[48:49], v[58:59], 0, v[162:163]
	v_lshl_add_u64 v[54:55], s[10:11], 0, v[52:53]
	global_load_dwordx4 v[48:51], v[48:49], off
	s_nop 0
	global_load_dwordx2 v[92:93], v[54:55], off nt
	v_lshl_add_u64 v[54:55], s[14:15], 0, v[52:53]
	v_lshl_add_u64 v[60:61], s[12:13], 0, v[52:53]
	v_lshl_add_u64 v[52:53], s[26:27], 0, v[52:53]
	global_load_dwordx2 v[94:95], v[54:55], off nt
	global_load_dwordx2 v[90:91], v[60:61], off nt
	global_load_dwordx2 v[88:89], v[52:53], off nt
	v_or_b32_e32 v54, v56, v146
	v_mov_b32_e32 v55, v57
	v_lshlrev_b64 v[60:61], 1, v[54:55]
	v_lshl_add_u64 v[52:53], v[58:59], 0, v[160:161]
	v_lshl_add_u64 v[62:63], s[10:11], 0, v[60:61]
	v_or_b32_e32 v56, v56, v148
	global_load_dwordx4 v[52:55], v[52:53], off
	s_nop 0
	global_load_dwordx2 v[84:85], v[62:63], off nt
	v_lshl_add_u64 v[62:63], s[14:15], 0, v[60:61]
	v_lshl_add_u64 v[72:73], s[12:13], 0, v[60:61]
	v_lshl_add_u64 v[60:61], s[26:27], 0, v[60:61]
	v_lshlrev_b64 v[56:57], 1, v[56:57]
	global_load_dwordx2 v[86:87], v[62:63], off nt
	global_load_dwordx2 v[82:83], v[72:73], off nt
	global_load_dwordx2 v[80:81], v[60:61], off nt
	v_lshl_add_u64 v[60:61], v[58:59], 0, v[158:159]
	v_lshl_add_u64 v[72:73], s[10:11], 0, v[56:57]
	global_load_dwordx4 v[60:63], v[60:61], off
	s_nop 0
	global_load_dwordx2 v[76:77], v[72:73], off nt
	v_lshl_add_u64 v[72:73], s[14:15], 0, v[56:57]
	v_lshl_add_u64 v[74:75], s[12:13], 0, v[56:57]
	v_lshl_add_u64 v[56:57], s[26:27], 0, v[56:57]
	global_load_dwordx2 v[78:79], v[72:73], off nt
	s_nop 0
	global_load_dwordx2 v[74:75], v[74:75], off nt
	s_nop 0
	global_load_dwordx2 v[72:73], v[56:57], off nt
	v_lshl_add_u64 v[56:57], v[58:59], 0, v[156:157]
	global_load_dwordx4 v[56:59], v[56:57], off
	s_waitcnt vmcnt(39)
	v_lshlrev_b32_e32 v166, 16, v100
	v_and_b32_e32 v167, 0xffff0000, v100
	s_waitcnt vmcnt(38)
	v_lshlrev_b32_e32 v168, 16, v102
	v_and_b32_e32 v169, 0xffff0000, v102
	v_lshlrev_b32_e32 v100, 16, v101
	v_and_b32_e32 v101, 0xffff0000, v101
	v_lshlrev_b32_e32 v102, 16, v103
	v_and_b32_e32 v103, 0xffff0000, v103
	v_pk_add_f32 v[166:167], v[166:167], v[168:169]
	s_waitcnt vmcnt(37)
	v_lshlrev_b32_e32 v168, 16, v104
	v_and_b32_e32 v169, 0xffff0000, v104
	s_waitcnt vmcnt(36)
	v_lshlrev_b32_e32 v170, 16, v106
	v_and_b32_e32 v171, 0xffff0000, v106
	v_pk_add_f32 v[100:101], v[100:101], v[102:103]
	v_lshlrev_b32_e32 v102, 16, v105
	v_and_b32_e32 v103, 0xffff0000, v105
	v_lshlrev_b32_e32 v104, 16, v107
	v_and_b32_e32 v105, 0xffff0000, v107
	v_pk_add_f32 v[168:169], v[168:169], v[170:171]
	v_pk_add_f32 v[102:103], v[102:103], v[104:105]
	v_pk_add_f32 v[166:167], v[166:167], v[168:169]
	v_pk_add_f32 v[168:169], v[100:101], v[102:103]
	s_waitcnt vmcnt(34)
	v_lshlrev_b32_e32 v100, 16, v108
	v_and_b32_e32 v101, 0xffff0000, v108
	s_waitcnt vmcnt(33)
	v_lshlrev_b32_e32 v102, 16, v110
	v_and_b32_e32 v103, 0xffff0000, v110
	v_pk_add_f32 v[100:101], v[100:101], v[102:103]
	s_waitcnt vmcnt(32)
	v_lshlrev_b32_e32 v102, 16, v112
	v_and_b32_e32 v103, 0xffff0000, v112
	s_waitcnt vmcnt(31)
	v_lshlrev_b32_e32 v104, 16, v114
	v_and_b32_e32 v105, 0xffff0000, v114
	v_pk_add_f32 v[102:103], v[102:103], v[104:105]
	v_lshlrev_b32_e32 v104, 16, v115
	v_pk_add_f32 v[170:171], v[100:101], v[102:103]
	v_lshlrev_b32_e32 v100, 16, v109
	v_and_b32_e32 v101, 0xffff0000, v109
	v_lshlrev_b32_e32 v102, 16, v111
	v_and_b32_e32 v103, 0xffff0000, v111
	v_pk_add_f32 v[100:101], v[100:101], v[102:103]
	v_lshlrev_b32_e32 v102, 16, v113
	v_and_b32_e32 v103, 0xffff0000, v113
	v_and_b32_e32 v105, 0xffff0000, v115
	v_pk_add_f32 v[102:103], v[102:103], v[104:105]
	s_waitcnt vmcnt(26)
	v_lshlrev_b32_e32 v104, 16, v122
	v_pk_add_f32 v[172:173], v[100:101], v[102:103]
	v_lshlrev_b32_e32 v100, 16, v116
	v_and_b32_e32 v101, 0xffff0000, v116
	v_lshlrev_b32_e32 v102, 16, v118
	v_and_b32_e32 v103, 0xffff0000, v118
	v_pk_add_f32 v[100:101], v[100:101], v[102:103]
	v_lshlrev_b32_e32 v102, 16, v120
	v_and_b32_e32 v103, 0xffff0000, v120
	v_and_b32_e32 v105, 0xffff0000, v122
	v_pk_add_f32 v[102:103], v[102:103], v[104:105]
	v_lshlrev_b32_e32 v104, 16, v123
	v_pk_add_f32 v[174:175], v[100:101], v[102:103]
	v_lshlrev_b32_e32 v100, 16, v117
	v_and_b32_e32 v101, 0xffff0000, v117
	v_lshlrev_b32_e32 v102, 16, v119
	v_and_b32_e32 v103, 0xffff0000, v119
	v_pk_add_f32 v[100:101], v[100:101], v[102:103]
	v_lshlrev_b32_e32 v102, 16, v121
	v_and_b32_e32 v103, 0xffff0000, v121
	v_and_b32_e32 v105, 0xffff0000, v123
	v_pk_add_f32 v[102:103], v[102:103], v[104:105]
	s_waitcnt vmcnt(21)
	v_lshlrev_b32_e32 v104, 16, v182
	v_pk_add_f32 v[176:177], v[100:101], v[102:103]
	v_mov_b32_e32 v102, v175
	v_mov_b32_e32 v103, v177
	v_mov_b32_e32 v100, v174
	v_mov_b32_e32 v101, v176
	v_pk_mul_f32 v[102:103], v[102:103], v[102:103]
	v_and_b32_e32 v105, 0xffff0000, v182
	v_pk_fma_f32 v[100:101], v[100:101], v[100:101], v[102:103]
	v_lshlrev_b32_e32 v102, 16, v126
	v_pk_add_f32 v[192:193], v[100:101], v[100:101] op_sel:[0,1] op_sel_hi:[1,0]
	v_lshlrev_b32_e32 v100, 16, v124
	v_and_b32_e32 v101, 0xffff0000, v124
	v_and_b32_e32 v103, 0xffff0000, v126
	v_pk_add_f32 v[100:101], v[100:101], v[102:103]
	v_lshlrev_b32_e32 v102, 16, v180
	v_and_b32_e32 v103, 0xffff0000, v180
	v_pk_add_f32 v[102:103], v[102:103], v[104:105]
	v_lshlrev_b32_e32 v104, 16, v183
	v_pk_add_f32 v[178:179], v[100:101], v[102:103]
	v_lshlrev_b32_e32 v100, 16, v125
	v_and_b32_e32 v101, 0xffff0000, v125
	v_lshlrev_b32_e32 v102, 16, v127
	v_and_b32_e32 v103, 0xffff0000, v127
	v_pk_add_f32 v[100:101], v[100:101], v[102:103]
	v_lshlrev_b32_e32 v102, 16, v181
	v_and_b32_e32 v103, 0xffff0000, v181
	v_and_b32_e32 v105, 0xffff0000, v183
	v_pk_add_f32 v[102:103], v[102:103], v[104:105]
	s_waitcnt vmcnt(16)
	v_lshlrev_b32_e32 v104, 16, v96
	v_pk_add_f32 v[180:181], v[100:101], v[102:103]
	v_mul_f32_e32 v100, v179, v179
	v_pk_fma_f32 v[198:199], v[178:179], v[178:179], v[100:101] op_sel_hi:[1,1,0]
	v_mul_f32_e32 v100, v181, v181
	v_pk_fma_f32 v[200:201], v[180:181], v[180:181], v[100:101] op_sel_hi:[1,1,0]
	v_lshlrev_b32_e32 v100, 16, v184
	v_and_b32_e32 v101, 0xffff0000, v184
	v_lshlrev_b32_e32 v102, 16, v186
	v_and_b32_e32 v103, 0xffff0000, v186
	v_pk_add_f32 v[100:101], v[100:101], v[102:103]
	v_lshlrev_b32_e32 v102, 16, v98
	v_and_b32_e32 v103, 0xffff0000, v98
	v_and_b32_e32 v105, 0xffff0000, v96
	v_pk_add_f32 v[102:103], v[102:103], v[104:105]
	v_lshlrev_b32_e32 v98, 16, v99
	v_pk_add_f32 v[182:183], v[100:101], v[102:103]
	v_lshlrev_b32_e32 v100, 16, v185
	v_and_b32_e32 v101, 0xffff0000, v185
	v_lshlrev_b32_e32 v102, 16, v187
	v_and_b32_e32 v103, 0xffff0000, v187
	v_and_b32_e32 v99, 0xffff0000, v99
	v_lshlrev_b32_e32 v96, 16, v97
	v_and_b32_e32 v97, 0xffff0000, v97
	v_pk_add_f32 v[100:101], v[100:101], v[102:103]
	v_pk_add_f32 v[96:97], v[98:99], v[96:97]
	s_waitcnt vmcnt(13)
	v_lshlrev_b32_e32 v98, 16, v94
	v_pk_add_f32 v[184:185], v[100:101], v[96:97]
	v_lshlrev_b32_e32 v96, 16, v92
	v_and_b32_e32 v97, 0xffff0000, v92
	v_and_b32_e32 v99, 0xffff0000, v94
	v_pk_add_f32 v[96:97], v[96:97], v[98:99]
	s_waitcnt vmcnt(12)
	v_lshlrev_b32_e32 v98, 16, v90
	v_and_b32_e32 v99, 0xffff0000, v90
	s_waitcnt vmcnt(11)
	v_lshlrev_b32_e32 v100, 16, v88
	v_and_b32_e32 v101, 0xffff0000, v88
	v_lshlrev_b32_e32 v92, 16, v93
	v_and_b32_e32 v93, 0xffff0000, v93
	v_lshlrev_b32_e32 v94, 16, v95
	v_and_b32_e32 v95, 0xffff0000, v95
	v_lshlrev_b32_e32 v90, 16, v91
	v_and_b32_e32 v91, 0xffff0000, v91
	v_lshlrev_b32_e32 v88, 16, v89
	v_and_b32_e32 v89, 0xffff0000, v89
	v_pk_add_f32 v[98:99], v[98:99], v[100:101]
	v_pk_add_f32 v[92:93], v[92:93], v[94:95]
	v_pk_add_f32 v[88:89], v[90:91], v[88:89]
	v_pk_add_f32 v[186:187], v[96:97], v[98:99]
	v_pk_add_f32 v[188:189], v[92:93], v[88:89]
	v_mov_b32_e32 v90, v187
	v_mov_b32_e32 v91, v189
	v_mov_b32_e32 v88, v186
	v_mov_b32_e32 v89, v188
	v_pk_mul_f32 v[90:91], v[90:91], v[90:91]
	s_waitcnt vmcnt(6)
	v_lshlrev_b32_e32 v92, 16, v80
	v_pk_fma_f32 v[88:89], v[88:89], v[88:89], v[90:91]
	v_lshlrev_b32_e32 v90, 16, v86
	v_pk_add_f32 v[206:207], v[88:89], v[88:89] op_sel:[0,1] op_sel_hi:[1,0]
	v_lshlrev_b32_e32 v88, 16, v84
	v_and_b32_e32 v89, 0xffff0000, v84
	v_and_b32_e32 v91, 0xffff0000, v86
	v_pk_add_f32 v[88:89], v[88:89], v[90:91]
	v_lshlrev_b32_e32 v90, 16, v82
	v_and_b32_e32 v91, 0xffff0000, v82
	v_and_b32_e32 v93, 0xffff0000, v80
	v_pk_add_f32 v[90:91], v[90:91], v[92:93]
	v_lshlrev_b32_e32 v84, 16, v85
	v_and_b32_e32 v85, 0xffff0000, v85
	v_lshlrev_b32_e32 v86, 16, v87
	v_and_b32_e32 v87, 0xffff0000, v87
	v_lshlrev_b32_e32 v82, 16, v83
	v_and_b32_e32 v83, 0xffff0000, v83
	v_lshlrev_b32_e32 v80, 16, v81
	v_and_b32_e32 v81, 0xffff0000, v81
	v_pk_add_f32 v[190:191], v[88:89], v[90:91]
	v_pk_add_f32 v[84:85], v[84:85], v[86:87]
	v_pk_add_f32 v[80:81], v[82:83], v[80:81]
	s_waitcnt vmcnt(3)
	v_lshlrev_b32_e32 v82, 16, v78
	v_pk_add_f32 v[194:195], v[84:85], v[80:81]
	v_mul_f32_e32 v80, v191, v191
	v_pk_fma_f32 v[208:209], v[190:191], v[190:191], v[80:81] op_sel_hi:[1,1,0]
	v_mul_f32_e32 v80, v195, v195
	v_pk_fma_f32 v[210:211], v[194:195], v[194:195], v[80:81] op_sel_hi:[1,1,0]
	v_lshlrev_b32_e32 v80, 16, v76
	v_and_b32_e32 v81, 0xffff0000, v76
	v_and_b32_e32 v83, 0xffff0000, v78
	v_pk_add_f32 v[80:81], v[80:81], v[82:83]
	s_waitcnt vmcnt(2)
	v_lshlrev_b32_e32 v82, 16, v74
	v_and_b32_e32 v83, 0xffff0000, v74
	s_waitcnt vmcnt(1)
	v_lshlrev_b32_e32 v84, 16, v72
	v_and_b32_e32 v85, 0xffff0000, v72
	v_lshlrev_b32_e32 v76, 16, v77
	v_and_b32_e32 v77, 0xffff0000, v77
	v_lshlrev_b32_e32 v78, 16, v79
	v_and_b32_e32 v79, 0xffff0000, v79
	v_lshlrev_b32_e32 v74, 16, v75
	v_and_b32_e32 v75, 0xffff0000, v75
	v_lshlrev_b32_e32 v72, 16, v73
	v_and_b32_e32 v73, 0xffff0000, v73
	v_pk_add_f32 v[82:83], v[82:83], v[84:85]
	v_pk_add_f32 v[76:77], v[76:77], v[78:79]
	v_pk_add_f32 v[72:73], v[74:75], v[72:73]
	v_pk_add_f32 v[196:197], v[80:81], v[82:83]
	v_pk_add_f32 v[212:213], v[76:77], v[72:73]
	v_pk_mul_f32 v[202:203], v[182:183], v[182:183]
	v_pk_mul_f32 v[204:205], v[184:185], v[184:185]
	v_pk_mul_f32 v[214:215], v[196:197], v[196:197]
	v_pk_mul_f32 v[216:217], v[212:213], v[212:213]
	v_lshl_add_u64 v[218:219], v[64:65], 0, s[54:55]
	v_lshl_add_u64 v[64:65], v[64:65], 0, s[56:57]
	v_lshl_add_u64 v[72:73], v[218:219], 0, v[134:135]
	v_lshl_add_u64 v[74:75], v[64:65], 0, v[134:135]
	global_load_dwordx4 v[120:123], v[72:73], off
	global_load_dwordx4 v[124:127], v[74:75], off
	v_lshl_add_u64 v[72:73], v[218:219], 0, v[66:67]
	v_lshl_add_u64 v[66:67], v[64:65], 0, v[66:67]
	global_load_dwordx4 v[112:115], v[72:73], off
	global_load_dwordx4 v[116:119], v[66:67], off
	v_lshl_add_u64 v[66:67], v[218:219], 0, v[68:69]
	v_lshl_add_u64 v[68:69], v[64:65], 0, v[68:69]
	global_load_dwordx4 v[104:107], v[66:67], off
	global_load_dwordx4 v[108:111], v[68:69], off
	v_lshl_add_u64 v[66:67], v[218:219], 0, v[70:71]
	v_lshl_add_u64 v[68:69], v[64:65], 0, v[70:71]
	global_load_dwordx4 v[96:99], v[66:67], off
	global_load_dwordx4 v[100:103], v[68:69], off
	v_lshl_add_u64 v[66:67], v[218:219], 0, v[162:163]
	v_lshl_add_u64 v[68:69], v[64:65], 0, v[162:163]
	global_load_dwordx4 v[88:91], v[66:67], off
	global_load_dwordx4 v[92:95], v[68:69], off
	v_lshl_add_u64 v[66:67], v[218:219], 0, v[160:161]
	v_lshl_add_u64 v[68:69], v[64:65], 0, v[160:161]
	global_load_dwordx4 v[80:83], v[66:67], off
	global_load_dwordx4 v[84:87], v[68:69], off
	v_lshl_add_u64 v[66:67], v[218:219], 0, v[158:159]
	v_lshl_add_u64 v[68:69], v[64:65], 0, v[158:159]
	global_load_dwordx4 v[72:75], v[66:67], off
	global_load_dwordx4 v[76:79], v[68:69], off
	v_lshl_add_u64 v[66:67], v[218:219], 0, v[156:157]
	v_lshl_add_u64 v[68:69], v[64:65], 0, v[156:157]
	global_load_dwordx4 v[64:67], v[66:67], off
	s_nop 0
	global_load_dwordx4 v[68:71], v[68:69], off
	v_mov_b32_e32 v222, v169
	v_mov_b32_e32 v223, v173
	v_mov_b32_e32 v218, v167
	v_mov_b32_e32 v219, v171
	v_mov_b32_e32 v220, v168
	v_mov_b32_e32 v221, v172
	v_pk_mul_f32 v[222:223], v[222:223], v[222:223]
	v_pk_mul_f32 v[218:219], v[218:219], v[218:219]
	v_pk_fma_f32 v[220:221], v[220:221], v[220:221], v[222:223]
	v_mov_b32_e32 v222, v166
	v_mov_b32_e32 v223, v170
	v_pk_fma_f32 v[218:219], v[222:223], v[222:223], v[218:219]
	v_mov_b32_e32 v199, v204
	v_pk_add_f32 v[218:219], v[218:219], v[220:221]
	v_mov_b32_e32 v201, v205
	v_pk_add_f32 v[218:219], v[218:219], v[218:219] op_sel:[0,1] op_sel_hi:[1,0]
	v_mov_b32_e32 v193, v203
	v_mov_b32_e32 v219, v202
	v_pk_add_f32 v[198:199], v[198:199], v[200:201]
	v_pk_add_f32 v[192:193], v[218:219], v[192:193]
	v_mov_b32_e32 v209, v216
	v_pk_add_f32 v[192:193], v[192:193], v[198:199]
	v_mov_b32_e32 v211, v217
	v_pk_add_f32 v[192:193], v[192:193], v[192:193] op_sel:[0,1] op_sel_hi:[1,0]
	v_mov_b32_e32 v207, v215
	v_mov_b32_e32 v193, v214
	v_pk_add_f32 v[198:199], v[208:209], v[210:211]
	v_pk_add_f32 v[192:193], v[192:193], v[206:207]
	s_nop 0
	v_pk_add_f32 v[192:193], v[192:193], v[198:199]
	s_nop 0
	v_add_f32_e32 v147, v192, v193
	ds_bpermute_b32 v149, v129, v147
	v_lshl_add_u64 v[164:165], s[48:49], 0, v[164:165]
	v_lshl_add_u64 v[192:193], v[164:165], 0, v[134:135]
	v_lshl_add_u64 v[162:163], v[164:165], 0, v[162:163]
	s_waitcnt lgkmcnt(0)
	v_add_f32_e32 v147, v147, v149
	ds_bpermute_b32 v149, v133, v147
	s_waitcnt lgkmcnt(0)
	v_add_f32_e32 v147, v147, v149
	ds_bpermute_b32 v149, v137, v147
	s_waitcnt lgkmcnt(0)
	v_add_f32_e32 v147, v147, v149
	ds_bpermute_b32 v149, v139, v147
	s_waitcnt lgkmcnt(0)
	v_add_f32_e32 v147, v147, v149
	ds_bpermute_b32 v149, v141, v147
	s_waitcnt lgkmcnt(0)
	v_add_f32_e32 v147, v147, v149
	ds_bpermute_b32 v149, v143, v147
	s_waitcnt lgkmcnt(0)
	v_add_f32_e32 v147, v147, v149
	v_fmamk_f32 v147, v147, 0x3a000000, v145
	v_mul_f32_e32 v149, 0x4b800000, v147
	v_cmp_gt_f32_e32 vcc, s59, v147
	s_nop 1
	v_cndmask_b32_e32 v147, v147, v149, vcc
	v_rsq_f32_e32 v147, v147
	s_nop 0
	v_mul_f32_e32 v134, 0x45800000, v147
	v_cndmask_b32_e32 v134, v147, v134, vcc
	v_pk_mul_f32 v[166:167], v[166:167], v[134:135] op_sel_hi:[1,0]
	v_pk_mul_f32 v[168:169], v[168:169], v[134:135] op_sel_hi:[1,0]
	v_pk_mul_f32 v[186:187], v[186:187], v[134:135] op_sel_hi:[1,0]
	v_pk_fma_f32 v[24:25], v[32:33], v[166:167], v[24:25]
	v_pk_mul_f32 v[32:33], v[188:189], v[134:135] op_sel_hi:[1,0]
	v_pk_mul_f32 v[170:171], v[170:171], v[134:135] op_sel_hi:[1,0]
	v_pk_mul_f32 v[172:173], v[172:173], v[134:135] op_sel_hi:[1,0]
	v_pk_mul_f32 v[174:175], v[174:175], v[134:135] op_sel_hi:[1,0]
	v_pk_mul_f32 v[176:177], v[176:177], v[134:135] op_sel_hi:[1,0]
	v_pk_mul_f32 v[178:179], v[178:179], v[134:135] op_sel_hi:[1,0]
	v_pk_mul_f32 v[180:181], v[180:181], v[134:135] op_sel_hi:[1,0]
	v_pk_mul_f32 v[182:183], v[182:183], v[134:135] op_sel_hi:[1,0]
	v_pk_mul_f32 v[184:185], v[184:185], v[134:135] op_sel_hi:[1,0]
	v_pk_fma_f32 v[26:27], v[34:35], v[168:169], v[26:27]
	v_pk_fma_f32 v[10:11], v[54:55], v[32:33], v[10:11]
	v_pk_fma_f32 v[8:9], v[52:53], v[186:187], v[8:9]
	v_lshl_add_u64 v[32:33], v[164:165], 0, v[160:161]
	v_pk_fma_f32 v[22:23], v[38:39], v[172:173], v[22:23]
	v_pk_fma_f32 v[20:21], v[36:37], v[170:171], v[20:21]
	v_pk_fma_f32 v[18:19], v[42:43], v[176:177], v[18:19]
	v_pk_fma_f32 v[16:17], v[40:41], v[174:175], v[16:17]
	v_pk_fma_f32 v[14:15], v[46:47], v[180:181], v[14:15]
	v_pk_fma_f32 v[12:13], v[44:45], v[178:179], v[12:13]
	v_pk_fma_f32 v[30:31], v[50:51], v[184:185], v[30:31]
	v_pk_fma_f32 v[28:29], v[48:49], v[182:183], v[28:29]
	global_store_dwordx4 v[192:193], v[24:27], off
	global_store_dwordx4 v[192:193], v[20:23], off offset:1024
	global_store_dwordx4 v[192:193], v[16:19], off offset:2048
	global_store_dwordx4 v[192:193], v[12:15], off offset:3072
	global_store_dwordx4 v[162:163], v[28:31], off
	global_store_dwordx4 v[32:33], v[8:11], off
	v_pk_mul_f32 v[32:33], v[190:191], v[134:135] op_sel_hi:[1,0]
	v_pk_mul_f32 v[34:35], v[194:195], v[134:135] op_sel_hi:[1,0]
	v_pk_fma_f32 v[4:5], v[60:61], v[32:33], v[4:5]
	v_pk_fma_f32 v[6:7], v[62:63], v[34:35], v[6:7]
	v_lshl_add_u64 v[32:33], v[164:165], 0, v[158:159]
	global_store_dwordx4 v[32:33], v[4:7], off
	v_pk_mul_f32 v[32:33], v[196:197], v[134:135] op_sel_hi:[1,0]
	v_pk_mul_f32 v[34:35], v[212:213], v[134:135] op_sel_hi:[1,0]
	s_waitcnt vmcnt(23)
	v_pk_fma_f32 v[0:1], v[56:57], v[32:33], v[0:1]
	v_pk_fma_f32 v[2:3], v[58:59], v[34:35], v[2:3]
	v_lshl_add_u64 v[32:33], v[164:165], 0, v[156:157]
	global_store_dwordx4 v[32:33], v[0:3], off
	v_mov_b32_e32 v34, v25
	v_mov_b32_e32 v35, v21
	v_mov_b32_e32 v32, v24
	v_mov_b32_e32 v33, v20
	v_pk_mul_f32 v[34:35], v[34:35], v[34:35]
	v_mov_b32_e32 v36, v27
	v_mov_b32_e32 v37, v23
	v_pk_fma_f32 v[32:33], v[32:33], v[32:33], v[34:35]
	v_mov_b32_e32 v34, v26
	v_mov_b32_e32 v35, v22
	v_pk_mul_f32 v[36:37], v[36:37], v[36:37]
	v_readfirstlane_b32 s83, v237
	s_lshl_b32 s83, s83, 1
	s_add_u32 s83, s83, s86
	s_add_u32 s83, s83, s94
	s_lshl_b32 s83, s83, 3
	s_sub_u32 s84, s83, s82
	s_mov_b32 s82, s83
	s_mov_b32 s85, 0
	s_mov_b64 s[6:7], s[84:85]
	s_lshl_b64 s[28:29], s[84:85], 13
	v_lshl_add_u64 v[130:131], v[130:131], 0, s[6:7]
	v_pk_fma_f32 v[34:35], v[34:35], v[34:35], v[36:37]
	v_pk_mul_f32 v[36:37], v[16:17], v[16:17]
	v_pk_add_f32 v[32:33], v[32:33], v[34:35]
	v_pk_mul_f32 v[34:35], v[18:19], v[18:19]
	v_pk_add_f32 v[32:33], v[32:33], v[32:33] op_sel_hi:[0,1]
	v_pk_mov_b32 v[38:39], v[36:37], v[34:35] op_sel:[1,0]
	v_mov_b32_e32 v37, v35
	v_mul_f32_e32 v32, v12, v12
	v_pk_add_f32 v[34:35], v[38:39], v[36:37]
	v_pk_fma_f32 v[36:37], v[12:13], v[12:13], v[32:33] op_sel_hi:[1,1,0]
	v_mul_f32_e32 v32, v14, v14
	v_pk_add_f32 v[34:35], v[34:35], v[34:35] op_sel_hi:[0,1]
	v_pk_fma_f32 v[38:39], v[14:15], v[14:15], v[32:33] op_sel_hi:[1,1,0]
	v_mul_f32_e32 v36, v28, v28
	v_mul_f32_e32 v38, v29, v29
	v_mul_f32_e32 v34, v30, v30
	v_mul_f32_e32 v32, v31, v31
	v_pk_add_f32 v[36:37], v[36:37], v[38:39]
	v_pk_add_f32 v[32:33], v[34:35], v[32:33]
	v_pk_mul_f32 v[34:35], v[10:11], v[10:11]
	v_pk_add_f32 v[32:33], v[36:37], v[32:33]
	v_pk_mul_f32 v[36:37], v[8:9], v[8:9]
	v_pk_add_f32 v[32:33], v[32:33], v[32:33] op_sel_hi:[0,1]
	v_pk_mov_b32 v[38:39], v[36:37], v[34:35] op_sel:[1,0]
	v_mov_b32_e32 v37, v35
	v_mul_f32_e32 v32, v4, v4
	v_pk_add_f32 v[34:35], v[38:39], v[36:37]
	v_pk_fma_f32 v[36:37], v[4:5], v[4:5], v[32:33] op_sel_hi:[1,1,0]
	v_mul_f32_e32 v32, v6, v6
	v_pk_add_f32 v[34:35], v[34:35], v[34:35] op_sel_hi:[0,1]
	v_pk_fma_f32 v[38:39], v[6:7], v[6:7], v[32:33] op_sel_hi:[1,1,0]
	v_mul_f32_e32 v36, v0, v0
	v_mul_f32_e32 v38, v1, v1
	v_mul_f32_e32 v34, v2, v2
	v_mul_f32_e32 v32, v3, v3
	v_pk_add_f32 v[36:37], v[36:37], v[38:39]
	v_pk_add_f32 v[32:33], v[34:35], v[32:33]
	v_lshlrev_b64 v[34:35], 12, v[154:155]
	v_pk_add_f32 v[32:33], v[36:37], v[32:33]
	v_lshl_add_u64 v[152:153], v[152:153], 0, s[28:29]
	v_add_f32_e32 v32, v32, v33
	ds_bpermute_b32 v33, v129, v32
	s_waitcnt lgkmcnt(0)
	v_add_f32_e32 v32, v32, v33
	ds_bpermute_b32 v33, v133, v32
	s_waitcnt lgkmcnt(0)
	v_add_f32_e32 v32, v32, v33
	ds_bpermute_b32 v33, v137, v32
	s_waitcnt lgkmcnt(0)
	v_add_f32_e32 v32, v32, v33
	ds_bpermute_b32 v33, v139, v32
	s_waitcnt lgkmcnt(0)
	v_add_f32_e32 v32, v32, v33
	ds_bpermute_b32 v33, v141, v32
	s_waitcnt lgkmcnt(0)
	v_add_f32_e32 v32, v32, v33
	ds_bpermute_b32 v33, v143, v32
	s_waitcnt lgkmcnt(0)
	v_add_f32_e32 v32, v32, v33
	v_fmamk_f32 v32, v32, 0x3a000000, v145
	v_mul_f32_e32 v33, 0x4b800000, v32
	v_cmp_gt_f32_e32 vcc, s59, v32
	s_nop 1
	v_cndmask_b32_e32 v32, v32, v33, vcc
	v_rsq_f32_e32 v32, v32
	s_nop 0
	v_mul_f32_e32 v33, 0x45800000, v32
	v_cndmask_b32_e32 v32, v32, v33, vcc
	v_pk_mul_f32 v[24:25], v[24:25], v[32:33] op_sel_hi:[1,0]
	v_pk_mul_f32 v[26:27], v[26:27], v[32:33] op_sel_hi:[1,0]
	v_pk_mul_f32 v[12:13], v[12:13], v[32:33] op_sel_hi:[1,0]
	v_pk_mul_f32 v[14:15], v[14:15], v[32:33] op_sel_hi:[1,0]
	s_waitcnt vmcnt(22)
	v_pk_fma_f32 v[26:27], v[122:123], v[26:27], v[126:127]
	v_pk_fma_f32 v[24:25], v[120:121], v[24:25], v[124:125]
	s_waitcnt vmcnt(16)
	v_pk_fma_f32 v[14:15], v[98:99], v[14:15], v[102:103]
	v_pk_fma_f32 v[12:13], v[96:97], v[12:13], v[100:101]
	v_cvt_pk_bf16_f32 v24, v24, v25
	v_cvt_pk_bf16_f32 v25, v26, v27
	v_lshl_add_u64 v[26:27], v[150:151], 0, v[34:35]
	v_cvt_pk_bf16_f32 v12, v12, v13
	v_cvt_pk_bf16_f32 v13, v14, v15
	v_pk_mul_f32 v[20:21], v[20:21], v[32:33] op_sel_hi:[1,0]
	v_pk_mul_f32 v[22:23], v[22:23], v[32:33] op_sel_hi:[1,0]
	v_pk_mul_f32 v[16:17], v[16:17], v[32:33] op_sel_hi:[1,0]
	v_pk_mul_f32 v[18:19], v[18:19], v[32:33] op_sel_hi:[1,0]
	global_store_dwordx2 v[26:27], v[12:13], off offset:1536
	v_pk_mul_f32 v[12:13], v[28:29], v[32:33] op_sel_hi:[1,0]
	v_pk_mul_f32 v[14:15], v[30:31], v[32:33] op_sel_hi:[1,0]
	v_pk_mul_f32 v[8:9], v[8:9], v[32:33] op_sel_hi:[1,0]
	v_pk_mul_f32 v[10:11], v[10:11], v[32:33] op_sel_hi:[1,0]
	v_pk_mul_f32 v[4:5], v[4:5], v[32:33] op_sel_hi:[1,0]
	v_pk_mul_f32 v[6:7], v[6:7], v[32:33] op_sel_hi:[1,0]
	v_pk_mul_f32 v[0:1], v[0:1], v[32:33] op_sel_hi:[1,0]
	v_pk_mul_f32 v[2:3], v[2:3], v[32:33] op_sel_hi:[1,0]
	v_pk_fma_f32 v[22:23], v[114:115], v[22:23], v[118:119]
	v_pk_fma_f32 v[20:21], v[112:113], v[20:21], v[116:117]
	v_pk_fma_f32 v[18:19], v[106:107], v[18:19], v[110:111]
	v_pk_fma_f32 v[16:17], v[104:105], v[16:17], v[108:109]
	s_waitcnt vmcnt(15)
	v_pk_fma_f32 v[14:15], v[90:91], v[14:15], v[94:95]
	v_pk_fma_f32 v[12:13], v[88:89], v[12:13], v[92:93]
	s_waitcnt vmcnt(13)
	v_pk_fma_f32 v[10:11], v[82:83], v[10:11], v[86:87]
	v_pk_fma_f32 v[8:9], v[80:81], v[8:9], v[84:85]
	s_waitcnt vmcnt(11)
	v_pk_fma_f32 v[6:7], v[74:75], v[6:7], v[78:79]
	v_pk_fma_f32 v[4:5], v[72:73], v[4:5], v[76:77]
	s_waitcnt vmcnt(9)
	v_pk_fma_f32 v[2:3], v[66:67], v[2:3], v[70:71]
	v_pk_fma_f32 v[0:1], v[64:65], v[0:1], v[68:69]
	v_cmp_lt_i32_e32 vcc, s60, v130
	v_cvt_pk_bf16_f32 v20, v20, v21
	v_cvt_pk_bf16_f32 v21, v22, v23
	v_cvt_pk_bf16_f32 v16, v16, v17
	v_cvt_pk_bf16_f32 v17, v18, v19
	v_cvt_pk_bf16_f32 v12, v12, v13
	v_cvt_pk_bf16_f32 v13, v14, v15
	v_cvt_pk_bf16_f32 v8, v8, v9
	v_cvt_pk_bf16_f32 v9, v10, v11
	v_cvt_pk_bf16_f32 v4, v4, v5
	v_cvt_pk_bf16_f32 v5, v6, v7
	v_cvt_pk_bf16_f32 v0, v0, v1
	v_cvt_pk_bf16_f32 v1, v2, v3
	s_or_b64 s[30:31], vcc, s[30:31]
	global_store_dwordx2 v[26:27], v[24:25], off
	global_store_dwordx2 v[26:27], v[20:21], off offset:512
	global_store_dwordx2 v[26:27], v[16:17], off offset:1024
	global_store_dwordx2 v[26:27], v[12:13], off offset:2048
	global_store_dwordx2 v[26:27], v[8:9], off offset:2560
	global_store_dwordx2 v[26:27], v[4:5], off offset:3072
	global_store_dwordx2 v[26:27], v[0:1], off offset:3584
	s_andn2_b64 exec, exec, s[30:31]
	s_cbranch_execz .LBB0_742

.LT_dp_done:
	s_mul_i32 s87, s87, s72
	s_lshl_b32 s84, s84, 7
	s_add_u32 s87, s87, s84
	s_add_u32 s58, s54, s87
	s_addc_u32 s59, s55, 0
	global_load_dwordx4 v[48:51], v36, s[56:57] nt
	global_load_dwordx4 v[52:55], v37, s[56:57] nt
	global_load_dwordx4 v[56:59], v38, s[56:57] nt
	global_load_dwordx4 v[60:63], v39, s[56:57] nt
	global_load_dwordx4 v[64:67], v40, s[56:57] nt
	global_load_dwordx4 v[68:71], v41, s[56:57] nt
	global_load_dwordx4 v[72:75], v42, s[56:57] nt
	global_load_dwordx4 v[76:79], v43, s[56:57] nt

.LT_da_done:
	s_mul_i32 s87, s87, s72
	s_lshl_b32 s84, s84, 7
	s_add_u32 s87, s87, s84
	s_add_u32 s82, s54, s87
	s_addc_u32 s83, s55, 0
	global_load_dwordx4 v[80:83], v36, s[80:81] nt
	global_load_dwordx4 v[84:87], v37, s[80:81] nt
	global_load_dwordx4 v[88:91], v38, s[80:81] nt
	global_load_dwordx4 v[92:95], v39, s[80:81] nt
	global_load_dwordx4 v[96:99], v40, s[80:81] nt
	global_load_dwordx4 v[100:103], v41, s[80:81] nt
	global_load_dwordx4 v[104:107], v42, s[80:81] nt
	global_load_dwordx4 v[108:111], v43, s[80:81] nt
	s_waitcnt vmcnt(8)
	v_cvt_pk_bf16_f32 v112, v48, v52
	v_cvt_pk_bf16_f32 v113, v56, v60
	v_cvt_pk_bf16_f32 v114, v64, v68
	v_cvt_pk_bf16_f32 v115, v72, v76
	v_cvt_pk_bf16_f32 v116, v49, v53
	v_cvt_pk_bf16_f32 v117, v57, v61
	v_cvt_pk_bf16_f32 v118, v65, v69
	v_cvt_pk_bf16_f32 v119, v73, v77
	v_cvt_pk_bf16_f32 v120, v50, v54
	v_cvt_pk_bf16_f32 v121, v58, v62
	v_cvt_pk_bf16_f32 v122, v66, v70
	v_cvt_pk_bf16_f32 v123, v74, v78
	v_cvt_pk_bf16_f32 v124, v51, v55
	v_cvt_pk_bf16_f32 v125, v59, v63
	v_cvt_pk_bf16_f32 v126, v67, v71
	v_cvt_pk_bf16_f32 v127, v75, v79
	global_store_dwordx4 v44, v[112:115], s[58:59]
	global_store_dwordx4 v45, v[116:119], s[58:59]
	global_store_dwordx4 v46, v[120:123], s[58:59]
	global_store_dwordx4 v47, v[124:127], s[58:59]
	s_add_u32 s65, s65, s66
	s_cmp_ge_u32 s65, s68
	s_cbranch_scc1 .LT_lastB
	s_mul_hi_u32 s84, s65, s69
	s_mul_i32 s85, s84, s70
	s_sub_u32 s85, s65, s85
	s_mul_i32 s86, s84, s77
	s_lshl_b32 s87, s85, 7
	s_add_u32 s86, s86, s87
	s_add_u32 s56, s52, s86
	s_addc_u32 s57, s53, 0
	s_lshl_b32 s87, s85, 5
	s_cmp_eq_u32 s73, 0
	s_cbranch_scc1 .LT_db_done
	s_cmp_eq_u32 s73, 1
	s_cbranch_scc0 .LT_db_win
	s_lshr_b32 s87, s85, 2
	s_lshl_b32 s87, s87, 8
	s_and_b32 s88, s85, 3
	s_lshl_b32 s88, s88, 5
	s_add_u32 s87, s87, s88
	s_add_u32 s87, s87, s74
	s_branch .LT_db_done

.LT_db_done:
	s_mul_i32 s87, s87, s72
	s_lshl_b32 s84, s84, 7
	s_add_u32 s87, s87, s84
	s_add_u32 s58, s54, s87
	s_addc_u32 s59, s55, 0
	global_load_dwordx4 v[48:51], v36, s[56:57] nt
	global_load_dwordx4 v[52:55], v37, s[56:57] nt
	global_load_dwordx4 v[56:59], v38, s[56:57] nt
	global_load_dwordx4 v[60:63], v39, s[56:57] nt
	global_load_dwordx4 v[64:67], v40, s[56:57] nt
	global_load_dwordx4 v[68:71], v41, s[56:57] nt
	global_load_dwordx4 v[72:75], v42, s[56:57] nt
	global_load_dwordx4 v[76:79], v43, s[56:57] nt
	s_waitcnt vmcnt(8)
	v_cvt_pk_bf16_f32 v112, v80, v84
	v_cvt_pk_bf16_f32 v113, v88, v92
	v_cvt_pk_bf16_f32 v114, v96, v100
	v_cvt_pk_bf16_f32 v115, v104, v108
	v_cvt_pk_bf16_f32 v116, v81, v85
	v_cvt_pk_bf16_f32 v117, v89, v93
	v_cvt_pk_bf16_f32 v118, v97, v101
	v_cvt_pk_bf16_f32 v119, v105, v109
	v_cvt_pk_bf16_f32 v120, v82, v86
	v_cvt_pk_bf16_f32 v121, v90, v94
	v_cvt_pk_bf16_f32 v122, v98, v102
	v_cvt_pk_bf16_f32 v123, v106, v110
	v_cvt_pk_bf16_f32 v124, v83, v87
	v_cvt_pk_bf16_f32 v125, v91, v95
	v_cvt_pk_bf16_f32 v126, v99, v103
	v_cvt_pk_bf16_f32 v127, v107, v111
	global_store_dwordx4 v44, v[112:115], s[82:83]
	global_store_dwordx4 v45, v[116:119], s[82:83]
	global_store_dwordx4 v46, v[120:123], s[82:83]
	global_store_dwordx4 v47, v[124:127], s[82:83]
	s_branch .LT_loop

.LBB0_1155:
	s_waitcnt vmcnt(0)
	v_ashrrev_i32_e32 v2, 13, v4
	v_bfe_u32 v10, v4, 5, 8
	v_and_b32_e32 v9, 0x7c, v5
	v_and_b32_e32 v0, 7, v2
	v_lshl_or_b32 v11, v10, 7, v9
	v_lshlrev_b32_e32 v14, 5, v2
	v_cvt_f32_ubyte0_e32 v17, v0
	v_lshlrev_b32_e32 v0, 2, v11
	v_ashrrev_i32_e32 v15, 31, v14
	v_or_b32_e32 v16, 1, v14
	v_lshl_add_u64 v[78:79], s[4:5], 0, v[0:1]
	v_lshlrev_b64 v[80:81], 17, v[14:15]
	v_or_b32_e32 v18, 2, v14
	v_or_b32_e32 v20, 3, v14
	v_or_b32_e32 v22, 4, v14
	v_or_b32_e32 v24, 5, v14
	v_or_b32_e32 v26, 6, v14
	v_or_b32_e32 v28, 7, v14
	v_or_b32_e32 v30, 8, v14
	v_or_b32_e32 v32, 9, v14
	v_or_b32_e32 v34, 10, v14
	v_or_b32_e32 v36, 11, v14
	v_or_b32_e32 v38, 12, v14
	v_or_b32_e32 v40, 13, v14
	v_or_b32_e32 v42, 14, v14
	v_or_b32_e32 v44, 15, v14
	v_or_b32_e32 v46, 16, v14
	v_or_b32_e32 v48, 17, v14
	v_or_b32_e32 v50, 18, v14
	v_or_b32_e32 v52, 19, v14
	v_or_b32_e32 v54, 20, v14
	v_or_b32_e32 v56, 21, v14
	v_or_b32_e32 v58, 22, v14
	v_or_b32_e32 v60, 23, v14
	v_or_b32_e32 v62, 24, v14
	v_or_b32_e32 v64, 25, v14
	v_or_b32_e32 v66, 26, v14
	v_or_b32_e32 v68, 27, v14
	v_or_b32_e32 v70, 28, v14
	v_or_b32_e32 v72, 29, v14
	v_or_b32_e32 v74, 30, v14
	v_or_b32_e32 v76, 31, v14
	v_sub_f32_e32 v129, 0xc0a00000, v17
	v_ashrrev_i32_e32 v17, 31, v16
	v_lshlrev_b64 v[82:83], 16, v[14:15]
	v_lshl_add_u64 v[14:15], v[78:79], 0, v[80:81]
	v_lshlrev_b64 v[80:81], 17, v[16:17]
	v_lshlrev_b64 v[148:149], 16, v[16:17]
	global_load_dwordx4 v[14:17], v[14:15], off nt
	v_add_u32_e32 v4, s12, v4
	v_cmp_lt_i32_e32 vcc, s16, v4
	s_or_b64 s[10:11], vcc, s[10:11]
	v_cmp_gt_f32_e32 vcc, s14, v129
	v_ashrrev_i32_e32 v19, 31, v18
	v_ashrrev_i32_e32 v21, 31, v20
	v_ashrrev_i32_e32 v23, 31, v22
	v_ashrrev_i32_e32 v25, 31, v24
	v_ashrrev_i32_e32 v27, 31, v26
	v_ashrrev_i32_e32 v29, 31, v28
	v_ashrrev_i32_e32 v31, 31, v30
	v_ashrrev_i32_e32 v33, 31, v32
	v_ashrrev_i32_e32 v35, 31, v34
	v_ashrrev_i32_e32 v37, 31, v36
	v_ashrrev_i32_e32 v39, 31, v38
	v_ashrrev_i32_e32 v41, 31, v40
	v_lshlrev_b32_e32 v0, 1, v11
	v_cndmask_b32_e32 v11, 0, v6, vcc
	v_lshlrev_b64 v[84:85], 17, v[18:19]
	v_lshlrev_b64 v[86:87], 17, v[20:21]
	v_lshlrev_b64 v[88:89], 17, v[22:23]
	v_lshlrev_b64 v[90:91], 17, v[24:25]
	v_lshlrev_b64 v[92:93], 17, v[26:27]
	v_lshlrev_b64 v[94:95], 17, v[28:29]
	v_lshlrev_b64 v[96:97], 17, v[30:31]
	v_lshlrev_b64 v[98:99], 17, v[32:33]
	v_lshlrev_b64 v[100:101], 17, v[34:35]
	v_lshlrev_b64 v[102:103], 17, v[36:37]
	v_lshlrev_b64 v[104:105], 17, v[38:39]
	v_lshlrev_b64 v[106:107], 17, v[40:41]
	v_lshl_add_u64 v[146:147], s[6:7], 0, v[0:1]
	v_lshlrev_b64 v[18:19], 16, v[18:19]
	v_lshlrev_b64 v[20:21], 16, v[20:21]
	v_lshlrev_b64 v[22:23], 16, v[22:23]
	v_lshlrev_b64 v[24:25], 16, v[24:25]
	v_lshlrev_b64 v[26:27], 16, v[26:27]
	v_lshlrev_b64 v[28:29], 16, v[28:29]
	v_lshlrev_b64 v[30:31], 16, v[30:31]
	v_lshlrev_b64 v[32:33], 16, v[32:33]
	v_lshlrev_b64 v[34:35], 16, v[34:35]
	v_lshlrev_b64 v[36:37], 16, v[36:37]
	v_lshlrev_b64 v[38:39], 16, v[38:39]
	v_lshlrev_b64 v[40:41], 16, v[40:41]
	v_lshlrev_b32_e32 v0, 2, v10
	v_add_f32_e32 v129, v129, v11
	v_lshl_add_u64 v[10:11], v[78:79], 0, v[80:81]
	v_lshl_add_u64 v[80:81], v[78:79], 0, v[84:85]
	v_lshl_add_u64 v[84:85], v[78:79], 0, v[86:87]
	v_lshl_add_u64 v[86:87], v[78:79], 0, v[88:89]
	v_lshl_add_u64 v[88:89], v[78:79], 0, v[90:91]
	v_lshl_add_u64 v[90:91], v[78:79], 0, v[92:93]
	v_lshl_add_u64 v[152:153], v[146:147], 0, v[18:19]
	v_lshl_add_u64 v[154:155], v[146:147], 0, v[20:21]
	v_lshl_add_u64 v[156:157], v[146:147], 0, v[22:23]
	v_lshl_add_u64 v[158:159], v[146:147], 0, v[24:25]
	v_lshl_add_u64 v[160:161], v[146:147], 0, v[26:27]
	v_lshl_add_u64 v[162:163], v[146:147], 0, v[28:29]
	v_lshl_add_u64 v[164:165], v[146:147], 0, v[30:31]
	v_lshl_add_u64 v[166:167], v[146:147], 0, v[32:33]
	v_lshl_add_u64 v[168:169], v[146:147], 0, v[34:35]
	v_lshl_add_u64 v[170:171], v[146:147], 0, v[36:37]
	v_lshl_add_u64 v[172:173], v[146:147], 0, v[38:39]
	v_lshl_add_u64 v[174:175], v[146:147], 0, v[40:41]
	global_load_dwordx4 v[18:21], v[10:11], off nt
	global_load_dwordx4 v[22:25], v[80:81], off nt
	global_load_dwordx4 v[26:29], v[84:85], off nt
	global_load_dwordx4 v[30:33], v[86:87], off nt
	global_load_dwordx4 v[34:37], v[88:89], off nt
	global_load_dwordx4 v[38:41], v[90:91], off nt
	v_ashrrev_i32_e32 v43, 31, v42
	v_ashrrev_i32_e32 v45, 31, v44
	v_ashrrev_i32_e32 v47, 31, v46
	v_ashrrev_i32_e32 v49, 31, v48
	v_ashrrev_i32_e32 v51, 31, v50
	v_ashrrev_i32_e32 v53, 31, v52
	v_ashrrev_i32_e32 v55, 31, v54
	v_ashrrev_i32_e32 v57, 31, v56
	v_ashrrev_i32_e32 v59, 31, v58
	v_ashrrev_i32_e32 v61, 31, v60
	v_ashrrev_i32_e32 v63, 31, v62
	v_ashrrev_i32_e32 v65, 31, v64
	v_ashrrev_i32_e32 v67, 31, v66
	v_ashrrev_i32_e32 v69, 31, v68
	v_ashrrev_i32_e32 v71, 31, v70
	v_ashrrev_i32_e32 v73, 31, v72
	v_ashrrev_i32_e32 v75, 31, v74
	v_ashrrev_i32_e32 v77, 31, v76
	v_lshlrev_b64 v[108:109], 17, v[42:43]
	v_lshlrev_b64 v[110:111], 17, v[44:45]
	v_lshlrev_b64 v[112:113], 17, v[46:47]
	v_lshlrev_b64 v[114:115], 17, v[48:49]
	v_lshlrev_b64 v[116:117], 17, v[50:51]
	v_lshlrev_b64 v[118:119], 17, v[52:53]
	v_lshlrev_b64 v[120:121], 17, v[54:55]
	v_lshlrev_b64 v[122:123], 17, v[56:57]
	v_lshlrev_b64 v[124:125], 17, v[58:59]
	v_lshlrev_b64 v[126:127], 17, v[60:61]
	v_lshlrev_b64 v[130:131], 17, v[62:63]
	v_lshlrev_b64 v[132:133], 17, v[64:65]
	v_lshlrev_b64 v[134:135], 17, v[66:67]
	v_lshlrev_b64 v[136:137], 17, v[68:69]
	v_lshlrev_b64 v[138:139], 17, v[70:71]
	v_lshlrev_b64 v[140:141], 17, v[72:73]
	v_lshlrev_b64 v[142:143], 17, v[74:75]
	v_lshlrev_b64 v[144:145], 17, v[76:77]
	v_lshlrev_b64 v[42:43], 16, v[42:43]
	v_lshlrev_b64 v[44:45], 16, v[44:45]
	v_lshlrev_b64 v[46:47], 16, v[46:47]
	v_lshlrev_b64 v[48:49], 16, v[48:49]
	v_lshlrev_b64 v[50:51], 16, v[50:51]
	v_lshlrev_b64 v[52:53], 16, v[52:53]
	v_lshlrev_b64 v[54:55], 16, v[54:55]
	v_lshlrev_b64 v[56:57], 16, v[56:57]
	v_lshlrev_b64 v[58:59], 16, v[58:59]
	v_lshlrev_b64 v[60:61], 16, v[60:61]
	v_lshlrev_b64 v[62:63], 16, v[62:63]
	v_lshlrev_b64 v[64:65], 16, v[64:65]
	v_lshlrev_b64 v[66:67], 16, v[66:67]
	v_lshlrev_b64 v[68:69], 16, v[68:69]
	v_lshlrev_b64 v[70:71], 16, v[70:71]
	v_lshlrev_b64 v[72:73], 16, v[72:73]
	v_lshlrev_b64 v[74:75], 16, v[74:75]
	v_lshlrev_b64 v[76:77], 16, v[76:77]
	v_lshl_add_u64 v[92:93], v[78:79], 0, v[94:95]
	v_lshl_add_u64 v[94:95], v[78:79], 0, v[96:97]
	v_lshl_add_u64 v[96:97], v[78:79], 0, v[98:99]
	v_lshl_add_u64 v[98:99], v[78:79], 0, v[100:101]
	v_lshl_add_u64 v[100:101], v[78:79], 0, v[102:103]
	v_lshl_add_u64 v[102:103], v[78:79], 0, v[104:105]
	v_lshl_add_u64 v[104:105], v[78:79], 0, v[106:107]
	v_lshl_add_u64 v[106:107], v[78:79], 0, v[108:109]
	v_lshl_add_u64 v[108:109], v[78:79], 0, v[110:111]
	v_lshl_add_u64 v[110:111], v[78:79], 0, v[112:113]
	v_lshl_add_u64 v[112:113], v[78:79], 0, v[114:115]
	v_lshl_add_u64 v[114:115], v[78:79], 0, v[116:117]
	v_lshl_add_u64 v[116:117], v[78:79], 0, v[118:119]
	v_lshl_add_u64 v[118:119], v[78:79], 0, v[120:121]
	v_lshl_add_u64 v[120:121], v[78:79], 0, v[122:123]
	v_lshl_add_u64 v[122:123], v[78:79], 0, v[124:125]
	v_lshl_add_u64 v[124:125], v[78:79], 0, v[126:127]
	v_lshl_add_u64 v[126:127], v[78:79], 0, v[130:131]
	v_lshl_add_u64 v[130:131], v[78:79], 0, v[132:133]
	v_lshl_add_u64 v[132:133], v[78:79], 0, v[134:135]
	v_lshl_add_u64 v[134:135], v[78:79], 0, v[136:137]
	v_lshl_add_u64 v[136:137], v[78:79], 0, v[138:139]
	v_lshl_add_u64 v[138:139], v[78:79], 0, v[140:141]
	v_lshl_add_u64 v[140:141], v[78:79], 0, v[142:143]
	v_lshl_add_u64 v[142:143], v[78:79], 0, v[144:145]
	v_lshl_add_u64 v[150:151], v[146:147], 0, v[82:83]
	v_lshl_add_u64 v[148:149], v[146:147], 0, v[148:149]
	v_lshl_add_u64 v[176:177], v[146:147], 0, v[42:43]
	v_lshl_add_u64 v[178:179], v[146:147], 0, v[44:45]
	v_lshl_add_u64 v[180:181], v[146:147], 0, v[46:47]
	v_lshl_add_u64 v[182:183], v[146:147], 0, v[48:49]
	v_lshl_add_u64 v[184:185], v[146:147], 0, v[50:51]
	v_lshl_add_u64 v[186:187], v[146:147], 0, v[52:53]
	v_lshl_add_u64 v[188:189], v[146:147], 0, v[54:55]
	v_lshl_add_u64 v[190:191], v[146:147], 0, v[56:57]
	v_lshl_add_u64 v[192:193], v[146:147], 0, v[58:59]
	v_lshl_add_u64 v[194:195], v[146:147], 0, v[60:61]
	v_lshl_add_u64 v[196:197], v[146:147], 0, v[62:63]
	v_lshl_add_u64 v[198:199], v[146:147], 0, v[64:65]
	v_lshl_add_u64 v[200:201], v[146:147], 0, v[66:67]
	v_lshl_add_u64 v[202:203], v[146:147], 0, v[68:69]
	v_lshl_add_u64 v[204:205], v[146:147], 0, v[70:71]
	v_lshl_add_u64 v[206:207], v[146:147], 0, v[72:73]
	v_lshl_add_u64 v[208:209], v[146:147], 0, v[74:75]
	v_lshl_add_u64 v[146:147], v[146:147], 0, v[76:77]
	global_load_dwordx4 v[42:45], v[92:93], off nt
	global_load_dwordx4 v[46:49], v[94:95], off nt
	global_load_dwordx4 v[50:53], v[96:97], off nt
	global_load_dwordx4 v[54:57], v[98:99], off nt
	global_load_dwordx4 v[58:61], v[100:101], off nt
	global_load_dwordx4 v[62:65], v[102:103], off nt
	global_load_dwordx4 v[66:69], v[104:105], off nt
	global_load_dwordx4 v[70:73], v[106:107], off nt
	global_load_dwordx4 v[74:77], v[108:109], off nt
	global_load_dwordx4 v[78:81], v[110:111], off nt
	global_load_dwordx4 v[82:85], v[112:113], off nt
	global_load_dwordx4 v[86:89], v[114:115], off nt
	global_load_dwordx4 v[90:93], v[116:117], off nt
	global_load_dwordx4 v[94:97], v[118:119], off nt
	global_load_dwordx4 v[98:101], v[120:121], off nt
	global_load_dwordx4 v[102:105], v[122:123], off nt
	global_load_dwordx4 v[106:109], v[124:125], off nt
	global_load_dwordx4 v[110:113], v[126:127], off nt
	global_load_dwordx4 v[114:117], v[130:131], off nt
	s_nop 0
	global_load_dwordx4 v[118:121], v[132:133], off nt
	global_load_dwordx4 v[122:125], v[134:135], off nt
	s_nop 0
	global_load_dwordx4 v[130:133], v[136:137], off nt
	s_nop 0
	global_load_dwordx4 v[134:137], v[138:139], off nt
	s_nop 0
	global_load_dwordx4 v[138:141], v[140:141], off nt
	s_nop 0
	global_load_dwordx4 v[142:145], v[142:143], off nt
	v_ashrrev_i32_e32 v3, 31, v2
	v_lshlrev_b64 v[2:3], 17, v[2:3]
	v_lshl_add_u64 v[2:3], s[8:9], 0, v[2:3]
	v_lshl_add_u64 v[2:3], v[2:3], 0, v[0:1]
	v_lshlrev_b32_e32 v0, 10, v9
	v_exp_f32_e32 v9, v129
	v_cndmask_b32_e32 v210, 0, v7, vcc
	v_lshl_add_u64 v[2:3], v[2:3], 0, v[0:1]
	v_add_u32_e32 v5, s13, v5
	v_ldexp_f32 v0, v9, v210
	v_sub_f32_e32 v0, 1.0, v0
	v_cmp_gt_f32_e32 vcc, s15, v0
	global_store_dwordx2 v[150:151], v[12:13], off
	s_nop 0
	v_cndmask_b32_e64 v9, 0, 32, vcc
	v_ldexp_f32 v0, v0, v9
	v_log_f32_e32 v0, v0
	v_cndmask_b32_e32 v9, 0, v8, vcc
	v_sub_f32_e32 v0, v0, v9
	v_mul_f32_e32 v9, 0x43000000, v0
	v_cmp_gt_f32_e32 vcc, s14, v9
	s_nop 1
	v_cndmask_b32_e32 v9, 0, v6, vcc
	v_fmac_f32_e32 v9, 0x43000000, v0
	v_exp_f32_e32 v9, v9
	v_cndmask_b32_e32 v0, 0, v7, vcc
	v_ldexp_f32 v0, v9, v0
	s_waitcnt vmcnt(32)
	v_pk_fma_f32 v[10:11], v[0:1], 0, v[16:17] op_sel_hi:[0,0,1]
	v_pk_fma_f32 v[14:15], v[0:1], 0, v[14:15] op_sel_hi:[0,0,1]
	v_cvt_pk_bf16_f32 v16, v14, v15
	v_cvt_pk_bf16_f32 v17, v10, v11
	s_waitcnt vmcnt(31)
	v_pk_fma_f32 v[10:11], v[0:1], v[10:11], v[20:21] op_sel_hi:[0,1,1]
	v_pk_fma_f32 v[14:15], v[0:1], v[14:15], v[18:19] op_sel_hi:[0,1,1]
	global_store_dwordx2 v[148:149], v[16:17], off
	v_cvt_pk_bf16_f32 v16, v14, v15
	v_cvt_pk_bf16_f32 v17, v10, v11
	s_waitcnt vmcnt(31)
	v_pk_fma_f32 v[10:11], v[0:1], v[10:11], v[24:25] op_sel_hi:[0,1,1]
	v_pk_fma_f32 v[14:15], v[0:1], v[14:15], v[22:23] op_sel_hi:[0,1,1]
	global_store_dwordx2 v[152:153], v[16:17], off
	v_cvt_pk_bf16_f32 v16, v14, v15
	v_cvt_pk_bf16_f32 v17, v10, v11
	s_waitcnt vmcnt(31)
	v_pk_fma_f32 v[10:11], v[0:1], v[10:11], v[28:29] op_sel_hi:[0,1,1]
	v_pk_fma_f32 v[14:15], v[0:1], v[14:15], v[26:27] op_sel_hi:[0,1,1]
	global_store_dwordx2 v[154:155], v[16:17], off
	v_cvt_pk_bf16_f32 v16, v14, v15
	v_cvt_pk_bf16_f32 v17, v10, v11
	s_waitcnt vmcnt(31)
	v_pk_fma_f32 v[10:11], v[0:1], v[10:11], v[32:33] op_sel_hi:[0,1,1]
	v_pk_fma_f32 v[14:15], v[0:1], v[14:15], v[30:31] op_sel_hi:[0,1,1]
	global_store_dwordx2 v[156:157], v[16:17], off
	v_cvt_pk_bf16_f32 v16, v14, v15
	v_cvt_pk_bf16_f32 v17, v10, v11
	s_waitcnt vmcnt(31)
	v_pk_fma_f32 v[10:11], v[0:1], v[10:11], v[36:37] op_sel_hi:[0,1,1]
	v_pk_fma_f32 v[14:15], v[0:1], v[14:15], v[34:35] op_sel_hi:[0,1,1]
	global_store_dwordx2 v[158:159], v[16:17], off
	v_cvt_pk_bf16_f32 v16, v14, v15
	v_cvt_pk_bf16_f32 v17, v10, v11
	s_waitcnt vmcnt(31)
	v_pk_fma_f32 v[10:11], v[0:1], v[10:11], v[40:41] op_sel_hi:[0,1,1]
	v_pk_fma_f32 v[14:15], v[0:1], v[14:15], v[38:39] op_sel_hi:[0,1,1]
	global_store_dwordx2 v[160:161], v[16:17], off
	v_cvt_pk_bf16_f32 v16, v14, v15
	v_cvt_pk_bf16_f32 v17, v10, v11
	s_waitcnt vmcnt(31)
	v_pk_fma_f32 v[10:11], v[0:1], v[10:11], v[44:45] op_sel_hi:[0,1,1]
	v_pk_fma_f32 v[14:15], v[0:1], v[14:15], v[42:43] op_sel_hi:[0,1,1]
	global_store_dwordx2 v[162:163], v[16:17], off
	v_cvt_pk_bf16_f32 v16, v14, v15
	v_cvt_pk_bf16_f32 v17, v10, v11
	s_waitcnt vmcnt(31)
	v_pk_fma_f32 v[10:11], v[0:1], v[10:11], v[48:49] op_sel_hi:[0,1,1]
	v_pk_fma_f32 v[14:15], v[0:1], v[14:15], v[46:47] op_sel_hi:[0,1,1]
	global_store_dwordx2 v[164:165], v[16:17], off
	v_cvt_pk_bf16_f32 v16, v14, v15
	v_cvt_pk_bf16_f32 v17, v10, v11
	s_waitcnt vmcnt(31)
	v_pk_fma_f32 v[10:11], v[0:1], v[10:11], v[52:53] op_sel_hi:[0,1,1]
	v_pk_fma_f32 v[14:15], v[0:1], v[14:15], v[50:51] op_sel_hi:[0,1,1]
	global_store_dwordx2 v[166:167], v[16:17], off
	v_cvt_pk_bf16_f32 v16, v14, v15
	v_cvt_pk_bf16_f32 v17, v10, v11
	s_waitcnt vmcnt(31)
	v_pk_fma_f32 v[10:11], v[0:1], v[10:11], v[56:57] op_sel_hi:[0,1,1]
	v_pk_fma_f32 v[14:15], v[0:1], v[14:15], v[54:55] op_sel_hi:[0,1,1]
	global_store_dwordx2 v[168:169], v[16:17], off
	v_cvt_pk_bf16_f32 v16, v14, v15
	v_cvt_pk_bf16_f32 v17, v10, v11
	s_waitcnt vmcnt(31)
	v_pk_fma_f32 v[10:11], v[0:1], v[10:11], v[60:61] op_sel_hi:[0,1,1]
	v_pk_fma_f32 v[14:15], v[0:1], v[14:15], v[58:59] op_sel_hi:[0,1,1]
	global_store_dwordx2 v[170:171], v[16:17], off
	v_cvt_pk_bf16_f32 v16, v14, v15
	v_cvt_pk_bf16_f32 v17, v10, v11
	s_waitcnt vmcnt(31)
	v_pk_fma_f32 v[10:11], v[0:1], v[10:11], v[64:65] op_sel_hi:[0,1,1]
	v_pk_fma_f32 v[14:15], v[0:1], v[14:15], v[62:63] op_sel_hi:[0,1,1]
	global_store_dwordx2 v[172:173], v[16:17], off
	v_cvt_pk_bf16_f32 v16, v14, v15
	v_cvt_pk_bf16_f32 v17, v10, v11
	s_waitcnt vmcnt(31)
	v_pk_fma_f32 v[10:11], v[0:1], v[10:11], v[68:69] op_sel_hi:[0,1,1]
	v_pk_fma_f32 v[14:15], v[0:1], v[14:15], v[66:67] op_sel_hi:[0,1,1]
	global_store_dwordx2 v[174:175], v[16:17], off
	v_cvt_pk_bf16_f32 v16, v14, v15
	v_cvt_pk_bf16_f32 v17, v10, v11
	s_waitcnt vmcnt(31)
	v_pk_fma_f32 v[10:11], v[0:1], v[10:11], v[72:73] op_sel_hi:[0,1,1]
	v_pk_fma_f32 v[14:15], v[0:1], v[14:15], v[70:71] op_sel_hi:[0,1,1]
	global_store_dwordx2 v[176:177], v[16:17], off
	v_cvt_pk_bf16_f32 v16, v14, v15
	v_cvt_pk_bf16_f32 v17, v10, v11
	s_waitcnt vmcnt(31)
	v_pk_fma_f32 v[10:11], v[0:1], v[10:11], v[76:77] op_sel_hi:[0,1,1]
	v_pk_fma_f32 v[14:15], v[0:1], v[14:15], v[74:75] op_sel_hi:[0,1,1]
	global_store_dwordx2 v[178:179], v[16:17], off
	v_cvt_pk_bf16_f32 v16, v14, v15
	v_cvt_pk_bf16_f32 v17, v10, v11
	s_waitcnt vmcnt(31)
	v_pk_fma_f32 v[10:11], v[0:1], v[10:11], v[80:81] op_sel_hi:[0,1,1]
	v_pk_fma_f32 v[14:15], v[0:1], v[14:15], v[78:79] op_sel_hi:[0,1,1]
	global_store_dwordx2 v[180:181], v[16:17], off
	v_cvt_pk_bf16_f32 v16, v14, v15
	v_cvt_pk_bf16_f32 v17, v10, v11
	s_waitcnt vmcnt(31)
	v_pk_fma_f32 v[10:11], v[0:1], v[10:11], v[84:85] op_sel_hi:[0,1,1]
	v_pk_fma_f32 v[14:15], v[0:1], v[14:15], v[82:83] op_sel_hi:[0,1,1]
	global_store_dwordx2 v[182:183], v[16:17], off
	v_cvt_pk_bf16_f32 v16, v14, v15
	v_cvt_pk_bf16_f32 v17, v10, v11
	s_waitcnt vmcnt(31)
	v_pk_fma_f32 v[10:11], v[0:1], v[10:11], v[88:89] op_sel_hi:[0,1,1]
	v_pk_fma_f32 v[14:15], v[0:1], v[14:15], v[86:87] op_sel_hi:[0,1,1]
	global_store_dwordx2 v[184:185], v[16:17], off
	v_cvt_pk_bf16_f32 v16, v14, v15
	v_cvt_pk_bf16_f32 v17, v10, v11
	s_waitcnt vmcnt(31)
	v_pk_fma_f32 v[10:11], v[0:1], v[10:11], v[92:93] op_sel_hi:[0,1,1]
	v_pk_fma_f32 v[14:15], v[0:1], v[14:15], v[90:91] op_sel_hi:[0,1,1]
	global_store_dwordx2 v[186:187], v[16:17], off
	v_cvt_pk_bf16_f32 v16, v14, v15
	v_cvt_pk_bf16_f32 v17, v10, v11
	s_waitcnt vmcnt(31)
	v_pk_fma_f32 v[10:11], v[0:1], v[10:11], v[96:97] op_sel_hi:[0,1,1]
	v_pk_fma_f32 v[14:15], v[0:1], v[14:15], v[94:95] op_sel_hi:[0,1,1]
	global_store_dwordx2 v[188:189], v[16:17], off
	v_cvt_pk_bf16_f32 v16, v14, v15
	v_cvt_pk_bf16_f32 v17, v10, v11
	s_waitcnt vmcnt(31)
	v_pk_fma_f32 v[10:11], v[0:1], v[10:11], v[100:101] op_sel_hi:[0,1,1]
	v_pk_fma_f32 v[14:15], v[0:1], v[14:15], v[98:99] op_sel_hi:[0,1,1]
	global_store_dwordx2 v[190:191], v[16:17], off
	v_cvt_pk_bf16_f32 v16, v14, v15
	v_cvt_pk_bf16_f32 v17, v10, v11
	s_waitcnt vmcnt(31)
	v_pk_fma_f32 v[10:11], v[0:1], v[10:11], v[104:105] op_sel_hi:[0,1,1]
	v_pk_fma_f32 v[14:15], v[0:1], v[14:15], v[102:103] op_sel_hi:[0,1,1]
	global_store_dwordx2 v[192:193], v[16:17], off
	v_cvt_pk_bf16_f32 v16, v14, v15
	v_cvt_pk_bf16_f32 v17, v10, v11
	s_waitcnt vmcnt(31)
	v_pk_fma_f32 v[10:11], v[0:1], v[10:11], v[108:109] op_sel_hi:[0,1,1]
	v_pk_fma_f32 v[14:15], v[0:1], v[14:15], v[106:107] op_sel_hi:[0,1,1]
	global_store_dwordx2 v[194:195], v[16:17], off
	v_cvt_pk_bf16_f32 v16, v14, v15
	v_cvt_pk_bf16_f32 v17, v10, v11
	s_waitcnt vmcnt(31)
	v_pk_fma_f32 v[10:11], v[0:1], v[10:11], v[112:113] op_sel_hi:[0,1,1]
	v_pk_fma_f32 v[14:15], v[0:1], v[14:15], v[110:111] op_sel_hi:[0,1,1]
	global_store_dwordx2 v[196:197], v[16:17], off
	v_cvt_pk_bf16_f32 v16, v14, v15
	v_cvt_pk_bf16_f32 v17, v10, v11
	s_waitcnt vmcnt(31)
	v_pk_fma_f32 v[10:11], v[0:1], v[10:11], v[116:117] op_sel_hi:[0,1,1]
	v_pk_fma_f32 v[14:15], v[0:1], v[14:15], v[114:115] op_sel_hi:[0,1,1]
	global_store_dwordx2 v[198:199], v[16:17], off
	v_cvt_pk_bf16_f32 v16, v14, v15
	v_cvt_pk_bf16_f32 v17, v10, v11
	s_waitcnt vmcnt(31)
	v_pk_fma_f32 v[10:11], v[0:1], v[10:11], v[120:121] op_sel_hi:[0,1,1]
	v_pk_fma_f32 v[14:15], v[0:1], v[14:15], v[118:119] op_sel_hi:[0,1,1]
	global_store_dwordx2 v[200:201], v[16:17], off
	v_cvt_pk_bf16_f32 v16, v14, v15
	v_cvt_pk_bf16_f32 v17, v10, v11
	s_waitcnt vmcnt(31)
	v_pk_fma_f32 v[10:11], v[0:1], v[10:11], v[124:125] op_sel_hi:[0,1,1]
	v_pk_fma_f32 v[14:15], v[0:1], v[14:15], v[122:123] op_sel_hi:[0,1,1]
	global_store_dwordx2 v[202:203], v[16:17], off
	v_cvt_pk_bf16_f32 v16, v14, v15
	v_cvt_pk_bf16_f32 v17, v10, v11
	s_waitcnt vmcnt(31)
	v_pk_fma_f32 v[10:11], v[0:1], v[10:11], v[132:133] op_sel_hi:[0,1,1]
	v_pk_fma_f32 v[14:15], v[0:1], v[14:15], v[130:131] op_sel_hi:[0,1,1]
	global_store_dwordx2 v[204:205], v[16:17], off
	v_cvt_pk_bf16_f32 v16, v14, v15
	v_cvt_pk_bf16_f32 v17, v10, v11
	s_waitcnt vmcnt(31)
	v_pk_fma_f32 v[10:11], v[0:1], v[10:11], v[136:137] op_sel_hi:[0,1,1]
	v_pk_fma_f32 v[14:15], v[0:1], v[14:15], v[134:135] op_sel_hi:[0,1,1]
	global_store_dwordx2 v[206:207], v[16:17], off
	v_cvt_pk_bf16_f32 v16, v14, v15
	v_cvt_pk_bf16_f32 v17, v10, v11
	s_waitcnt vmcnt(31)
	v_pk_fma_f32 v[10:11], v[0:1], v[10:11], v[140:141] op_sel_hi:[0,1,1]
	v_pk_fma_f32 v[14:15], v[0:1], v[14:15], v[138:139] op_sel_hi:[0,1,1]
	global_store_dwordx2 v[208:209], v[16:17], off
	v_cvt_pk_bf16_f32 v16, v14, v15
	v_cvt_pk_bf16_f32 v17, v10, v11
	s_waitcnt vmcnt(31)
	v_pk_fma_f32 v[10:11], v[0:1], v[10:11], v[144:145] op_sel_hi:[0,1,1]
	v_pk_fma_f32 v[14:15], v[0:1], v[14:15], v[142:143] op_sel_hi:[0,1,1]
	global_store_dwordx2 v[146:147], v[16:17], off
	global_store_dword v[2:3], v14, off nt
	global_store_dword v[2:3], v15, off offset:1024 nt
	global_store_dword v[2:3], v10, off offset:2048 nt
	global_store_dword v[2:3], v11, off offset:3072 nt
	s_andn2_b64 exec, exec, s[10:11]
	s_cbranch_execnz .LBB0_1155

.LBB0_1625:
	s_mov_b64 s[80:81], exec
	s_mov_b64 exec, 1
	v_mov_b32_e32 v237, 1
	global_atomic_add v237, v236, v237, s[50:51] sc0
	s_mov_b64 exec, s[80:81]
	global_load_dwordx4 v[28:31], v[136:137], off offset:-4096
	global_load_dwordx4 v[24:27], v[136:137], off offset:-3072
	global_load_dwordx4 v[20:23], v[136:137], off offset:-2048
	global_load_dwordx4 v[16:19], v[136:137], off offset:-1024
	global_load_dwordx4 v[12:15], v[136:137], off
	global_load_dwordx4 v[8:11], v[136:137], off offset:1024
	global_load_dwordx4 v[4:7], v[136:137], off offset:2048
	global_load_dwordx4 v[0:3], v[136:137], off offset:3072
	v_add_u32_e32 v33, 0xffffe000, v130
	v_lshrrev_b32_e32 v33, 3, v33
	v_ashrrev_i32_e32 v32, 12, v130
	v_add_u32_e32 v33, 2, v33
	v_cmp_gt_i32_e32 vcc, s3, v130
	s_nop 1
	v_cndmask_b32_e32 v32, v33, v32, vcc
	v_mad_i64_i32 v[64:65], s[26:27], v32, s18, v[138:139]
	v_add_co_u32_e32 v50, vcc, s19, v134
	v_lshl_add_u64 v[48:49], v[64:65], 0, s[12:13]
	s_nop 0
	v_addc_co_u32_e32 v51, vcc, -1, v135, vcc
	v_add_co_u32_e32 v60, vcc, s20, v134
	v_lshl_add_u64 v[40:41], v[48:49], 0, v[132:133]
	s_nop 0
	v_addc_co_u32_e32 v61, vcc, -1, v135, vcc
	v_add_co_u32_e32 v62, vcc, s21, v134
	v_lshl_add_u64 v[42:43], v[48:49], 0, v[140:141]
	v_lshl_add_u64 v[52:53], v[48:49], 0, v[142:143]
	v_lshl_add_u64 v[54:55], v[48:49], 0, v[144:145]
	v_addc_co_u32_e32 v63, vcc, -1, v135, vcc
	global_load_dwordx4 v[36:39], v[40:41], off
	global_load_dwordx4 v[32:35], v[42:43], off
	global_load_dwordx2 v[82:83], v[50:51], off offset:-3584 nt
	global_load_dwordx2 v[84:85], v[50:51], off offset:-3072 nt
	global_load_dwordx2 v[86:87], v[50:51], off offset:-2560 nt
	global_load_dwordx2 v[88:89], v[50:51], off offset:-2048 nt
	global_load_dwordx2 v[90:91], v[60:61], off offset:-3584 nt
	global_load_dwordx2 v[92:93], v[60:61], off offset:-3072 nt
	global_load_dwordx2 v[94:95], v[60:61], off offset:-2560 nt
	global_load_dwordx2 v[96:97], v[60:61], off offset:-2048 nt
	global_load_dwordx2 v[98:99], v[62:63], off offset:-3584 nt
	global_load_dwordx2 v[100:101], v[62:63], off offset:-3072 nt
	global_load_dwordx2 v[102:103], v[62:63], off offset:-2560 nt
	global_load_dwordx2 v[104:105], v[62:63], off offset:-2048 nt
	global_load_dwordx2 v[106:107], v[134:135], off offset:-3584 nt
	global_load_dwordx2 v[108:109], v[134:135], off offset:-3072 nt
	global_load_dwordx2 v[110:111], v[134:135], off offset:-2560 nt
	global_load_dwordx2 v[112:113], v[134:135], off offset:-2048 nt
	global_load_dwordx4 v[44:47], v[52:53], off
	global_load_dwordx4 v[40:43], v[54:55], off
	v_lshl_add_u64 v[52:53], v[48:49], 0, v[146:147]
	v_lshl_add_u64 v[54:55], v[48:49], 0, v[148:149]
	global_load_dwordx4 v[56:59], v[52:53], off
	s_nop 0
	global_load_dwordx4 v[52:55], v[54:55], off
	s_nop 0
	global_load_dwordx2 v[116:117], v[50:51], off offset:-1536 nt
	global_load_dwordx2 v[118:119], v[50:51], off offset:-1024 nt
	global_load_dwordx2 v[74:75], v[50:51], off offset:-512 nt
	global_load_dwordx2 v[70:71], v[50:51], off nt
	global_load_dwordx2 v[120:121], v[60:61], off offset:-1536 nt
	global_load_dwordx2 v[122:123], v[60:61], off offset:-1024 nt
	global_load_dwordx2 v[80:81], v[60:61], off offset:-512 nt
	global_load_dwordx2 v[72:73], v[60:61], off nt
	global_load_dwordx2 v[124:125], v[62:63], off offset:-1536 nt
	global_load_dwordx2 v[126:127], v[62:63], off offset:-1024 nt
	global_load_dwordx2 v[76:77], v[62:63], off offset:-512 nt
	global_load_dwordx2 v[66:67], v[62:63], off nt
	global_load_dwordx2 v[172:173], v[134:135], off offset:-1536 nt
	global_load_dwordx2 v[178:179], v[134:135], off offset:-1024 nt
	global_load_dwordx2 v[78:79], v[134:135], off offset:-512 nt
	global_load_dwordx2 v[68:69], v[134:135], off nt
	v_lshl_add_u64 v[114:115], v[48:49], 0, v[150:151]
	v_lshl_add_u64 v[48:49], v[48:49], 0, v[152:153]
	global_load_dwordx4 v[60:63], v[114:115], off
	s_nop 0
	global_load_dwordx4 v[48:51], v[48:49], off
	s_waitcnt vmcnt(37)
	v_lshlrev_b32_e32 v114, 16, v82
	v_and_b32_e32 v115, 0xffff0000, v82
	s_waitcnt vmcnt(33)
	v_lshlrev_b32_e32 v154, 16, v90
	v_and_b32_e32 v155, 0xffff0000, v90
	v_lshlrev_b32_e32 v82, 16, v83
	v_and_b32_e32 v83, 0xffff0000, v83
	v_lshlrev_b32_e32 v90, 16, v91
	v_and_b32_e32 v91, 0xffff0000, v91
	v_pk_add_f32 v[114:115], v[114:115], v[154:155]
	s_waitcnt vmcnt(29)
	v_lshlrev_b32_e32 v154, 16, v98
	v_and_b32_e32 v155, 0xffff0000, v98
	v_pk_add_f32 v[82:83], v[82:83], v[90:91]
	v_lshlrev_b32_e32 v90, 16, v99
	v_and_b32_e32 v91, 0xffff0000, v99
	s_waitcnt vmcnt(25)
	v_lshlrev_b32_e32 v98, 16, v107
	v_and_b32_e32 v99, 0xffff0000, v107
	v_lshlrev_b32_e32 v156, 16, v106
	v_and_b32_e32 v157, 0xffff0000, v106
	v_pk_add_f32 v[90:91], v[90:91], v[98:99]
	v_pk_add_f32 v[154:155], v[154:155], v[156:157]
	v_pk_add_f32 v[156:157], v[82:83], v[90:91]
	v_lshlrev_b32_e32 v82, 16, v84
	v_and_b32_e32 v83, 0xffff0000, v84
	v_lshlrev_b32_e32 v90, 16, v92
	v_and_b32_e32 v91, 0xffff0000, v92
	v_pk_add_f32 v[82:83], v[82:83], v[90:91]
	v_lshlrev_b32_e32 v90, 16, v100
	v_and_b32_e32 v91, 0xffff0000, v100
	s_waitcnt vmcnt(24)
	v_lshlrev_b32_e32 v98, 16, v108
	v_and_b32_e32 v99, 0xffff0000, v108
	v_pk_add_f32 v[90:91], v[90:91], v[98:99]
	v_lshlrev_b32_e32 v84, 16, v93
	v_pk_add_f32 v[158:159], v[82:83], v[90:91]
	v_lshlrev_b32_e32 v82, 16, v85
	v_and_b32_e32 v83, 0xffff0000, v85
	v_and_b32_e32 v85, 0xffff0000, v93
	v_pk_add_f32 v[82:83], v[82:83], v[84:85]
	v_lshlrev_b32_e32 v84, 16, v101
	v_and_b32_e32 v85, 0xffff0000, v101
	v_lshlrev_b32_e32 v90, 16, v109
	v_and_b32_e32 v91, 0xffff0000, v109
	v_pk_add_f32 v[84:85], v[84:85], v[90:91]
	s_waitcnt vmcnt(23)
	v_lshlrev_b32_e32 v90, 16, v110
	v_pk_add_f32 v[160:161], v[82:83], v[84:85]
	v_lshlrev_b32_e32 v82, 16, v86
	v_and_b32_e32 v83, 0xffff0000, v86
	v_lshlrev_b32_e32 v84, 16, v94
	v_and_b32_e32 v85, 0xffff0000, v94
	v_pk_add_f32 v[82:83], v[82:83], v[84:85]
	v_lshlrev_b32_e32 v84, 16, v102
	v_and_b32_e32 v85, 0xffff0000, v102
	v_and_b32_e32 v91, 0xffff0000, v110
	v_pk_add_f32 v[84:85], v[84:85], v[90:91]
	v_lshlrev_b32_e32 v86, 16, v111
	v_pk_add_f32 v[162:163], v[82:83], v[84:85]
	v_lshlrev_b32_e32 v82, 16, v87
	v_and_b32_e32 v83, 0xffff0000, v87
	v_lshlrev_b32_e32 v84, 16, v95
	v_and_b32_e32 v85, 0xffff0000, v95
	v_pk_add_f32 v[82:83], v[82:83], v[84:85]
	v_lshlrev_b32_e32 v84, 16, v103
	v_and_b32_e32 v85, 0xffff0000, v103
	v_and_b32_e32 v87, 0xffff0000, v111
	v_pk_add_f32 v[84:85], v[84:85], v[86:87]
	s_waitcnt vmcnt(22)
	v_lshlrev_b32_e32 v86, 16, v112
	v_pk_add_f32 v[164:165], v[82:83], v[84:85]
	v_mov_b32_e32 v84, v163
	v_mov_b32_e32 v85, v165
	v_mov_b32_e32 v82, v162
	v_mov_b32_e32 v83, v164
	v_pk_mul_f32 v[84:85], v[84:85], v[84:85]
	v_and_b32_e32 v87, 0xffff0000, v112
	v_pk_fma_f32 v[82:83], v[82:83], v[82:83], v[84:85]
	v_lshlrev_b32_e32 v84, 16, v96
	v_pk_add_f32 v[176:177], v[82:83], v[82:83] op_sel:[0,1] op_sel_hi:[1,0]
	v_lshlrev_b32_e32 v82, 16, v88
	v_and_b32_e32 v83, 0xffff0000, v88
	v_and_b32_e32 v85, 0xffff0000, v96
	v_pk_add_f32 v[82:83], v[82:83], v[84:85]
	v_lshlrev_b32_e32 v84, 16, v104
	v_and_b32_e32 v85, 0xffff0000, v104
	v_pk_add_f32 v[84:85], v[84:85], v[86:87]
	v_lshlrev_b32_e32 v86, 16, v113
	v_pk_add_f32 v[166:167], v[82:83], v[84:85]
	v_lshlrev_b32_e32 v82, 16, v89
	v_and_b32_e32 v83, 0xffff0000, v89
	v_lshlrev_b32_e32 v84, 16, v97
	v_and_b32_e32 v85, 0xffff0000, v97
	v_pk_add_f32 v[82:83], v[82:83], v[84:85]
	v_lshlrev_b32_e32 v84, 16, v105
	v_and_b32_e32 v85, 0xffff0000, v105
	v_and_b32_e32 v87, 0xffff0000, v113
	v_pk_add_f32 v[84:85], v[84:85], v[86:87]
	s_waitcnt vmcnt(5)
	v_lshlrev_b32_e32 v86, 16, v172
	v_pk_add_f32 v[168:169], v[82:83], v[84:85]
	v_mul_f32_e32 v82, v167, v167
	v_pk_fma_f32 v[190:191], v[166:167], v[166:167], v[82:83] op_sel_hi:[1,1,0]
	v_mul_f32_e32 v82, v169, v169
	v_pk_fma_f32 v[192:193], v[168:169], v[168:169], v[82:83] op_sel_hi:[1,1,0]
	v_lshlrev_b32_e32 v82, 16, v116
	v_and_b32_e32 v83, 0xffff0000, v116
	v_lshlrev_b32_e32 v84, 16, v120
	v_and_b32_e32 v85, 0xffff0000, v120
	v_pk_add_f32 v[82:83], v[82:83], v[84:85]
	v_lshlrev_b32_e32 v84, 16, v124
	v_and_b32_e32 v85, 0xffff0000, v124
	v_and_b32_e32 v87, 0xffff0000, v172
	v_pk_add_f32 v[84:85], v[84:85], v[86:87]
	v_lshlrev_b32_e32 v86, 16, v173
	v_pk_add_f32 v[170:171], v[82:83], v[84:85]
	v_lshlrev_b32_e32 v82, 16, v117
	v_and_b32_e32 v83, 0xffff0000, v117
	v_lshlrev_b32_e32 v84, 16, v121
	v_and_b32_e32 v85, 0xffff0000, v121
	v_pk_add_f32 v[82:83], v[82:83], v[84:85]
	v_lshlrev_b32_e32 v84, 16, v125
	v_and_b32_e32 v85, 0xffff0000, v125
	v_and_b32_e32 v87, 0xffff0000, v173
	v_pk_add_f32 v[84:85], v[84:85], v[86:87]
	s_waitcnt vmcnt(4)
	v_lshlrev_b32_e32 v86, 16, v178
	v_pk_add_f32 v[172:173], v[82:83], v[84:85]
	v_lshlrev_b32_e32 v82, 16, v118
	v_and_b32_e32 v83, 0xffff0000, v118
	v_lshlrev_b32_e32 v84, 16, v122
	v_and_b32_e32 v85, 0xffff0000, v122
	v_pk_add_f32 v[82:83], v[82:83], v[84:85]
	v_lshlrev_b32_e32 v84, 16, v126
	v_and_b32_e32 v85, 0xffff0000, v126
	v_and_b32_e32 v87, 0xffff0000, v178
	v_pk_add_f32 v[84:85], v[84:85], v[86:87]
	v_lshlrev_b32_e32 v86, 16, v179
	v_pk_add_f32 v[174:175], v[82:83], v[84:85]
	v_lshlrev_b32_e32 v82, 16, v119
	v_and_b32_e32 v83, 0xffff0000, v119
	v_lshlrev_b32_e32 v84, 16, v123
	v_and_b32_e32 v85, 0xffff0000, v123
	v_pk_add_f32 v[82:83], v[82:83], v[84:85]
	v_lshlrev_b32_e32 v84, 16, v127
	v_and_b32_e32 v85, 0xffff0000, v127
	v_and_b32_e32 v87, 0xffff0000, v179
	v_pk_add_f32 v[84:85], v[84:85], v[86:87]
	s_waitcnt vmcnt(3)
	v_lshlrev_b32_e32 v86, 16, v78
	v_pk_add_f32 v[178:179], v[82:83], v[84:85]
	v_mov_b32_e32 v84, v175
	v_mov_b32_e32 v85, v179
	v_mov_b32_e32 v82, v174
	v_mov_b32_e32 v83, v178
	v_pk_mul_f32 v[84:85], v[84:85], v[84:85]
	v_and_b32_e32 v87, 0xffff0000, v78
	v_pk_fma_f32 v[82:83], v[82:83], v[82:83], v[84:85]
	v_lshlrev_b32_e32 v84, 16, v80
	v_pk_add_f32 v[198:199], v[82:83], v[82:83] op_sel:[0,1] op_sel_hi:[1,0]
	v_lshlrev_b32_e32 v82, 16, v74
	v_and_b32_e32 v83, 0xffff0000, v74
	v_and_b32_e32 v85, 0xffff0000, v80
	v_pk_add_f32 v[82:83], v[82:83], v[84:85]
	v_lshlrev_b32_e32 v84, 16, v76
	v_and_b32_e32 v85, 0xffff0000, v76
	v_pk_add_f32 v[84:85], v[84:85], v[86:87]
	v_lshlrev_b32_e32 v74, 16, v75
	v_and_b32_e32 v75, 0xffff0000, v75
	v_lshlrev_b32_e32 v80, 16, v81
	v_and_b32_e32 v81, 0xffff0000, v81
	v_lshlrev_b32_e32 v76, 16, v77
	v_and_b32_e32 v77, 0xffff0000, v77
	v_lshlrev_b32_e32 v78, 16, v79
	v_and_b32_e32 v79, 0xffff0000, v79
	v_pk_add_f32 v[180:181], v[82:83], v[84:85]
	v_pk_add_f32 v[74:75], v[74:75], v[80:81]
	v_pk_add_f32 v[76:77], v[76:77], v[78:79]
	s_waitcnt vmcnt(2)
	v_lshlrev_b32_e32 v78, 16, v68
	v_pk_add_f32 v[182:183], v[74:75], v[76:77]
	v_mul_f32_e32 v74, v181, v181
	v_pk_fma_f32 v[200:201], v[180:181], v[180:181], v[74:75] op_sel_hi:[1,1,0]
	v_mul_f32_e32 v74, v183, v183
	v_pk_fma_f32 v[202:203], v[182:183], v[182:183], v[74:75] op_sel_hi:[1,1,0]
	v_lshlrev_b32_e32 v74, 16, v70
	v_and_b32_e32 v75, 0xffff0000, v70
	v_lshlrev_b32_e32 v76, 16, v72
	v_and_b32_e32 v77, 0xffff0000, v72
	v_pk_add_f32 v[74:75], v[74:75], v[76:77]
	v_lshlrev_b32_e32 v76, 16, v66
	v_and_b32_e32 v77, 0xffff0000, v66
	v_and_b32_e32 v79, 0xffff0000, v68
	v_lshlrev_b32_e32 v70, 16, v71
	v_and_b32_e32 v71, 0xffff0000, v71
	v_lshlrev_b32_e32 v72, 16, v73
	v_and_b32_e32 v73, 0xffff0000, v73
	v_lshlrev_b32_e32 v66, 16, v67
	v_and_b32_e32 v67, 0xffff0000, v67
	v_lshlrev_b32_e32 v68, 16, v69
	v_and_b32_e32 v69, 0xffff0000, v69
	v_pk_add_f32 v[76:77], v[76:77], v[78:79]
	v_pk_add_f32 v[70:71], v[70:71], v[72:73]
	v_pk_add_f32 v[66:67], v[66:67], v[68:69]
	v_pk_add_f32 v[204:205], v[74:75], v[76:77]
	v_pk_add_f32 v[206:207], v[70:71], v[66:67]
	v_pk_add_f32 v[154:155], v[114:115], v[154:155]
	v_pk_mul_f32 v[194:195], v[170:171], v[170:171]
	v_pk_mul_f32 v[196:197], v[172:173], v[172:173]
	v_pk_mul_f32 v[208:209], v[204:205], v[204:205]
	v_pk_mul_f32 v[210:211], v[206:207], v[206:207]
	v_lshl_add_u64 v[120:121], v[64:65], 0, s[14:15]
	v_lshl_add_u64 v[122:123], v[64:65], 0, s[16:17]
	v_lshl_add_u64 v[64:65], v[120:121], 0, v[132:133]
	v_lshl_add_u64 v[68:69], v[122:123], 0, v[132:133]
	v_lshl_add_u64 v[72:73], v[120:121], 0, v[140:141]
	v_lshl_add_u64 v[76:77], v[122:123], 0, v[140:141]
	v_lshl_add_u64 v[80:81], v[120:121], 0, v[142:143]
	v_lshl_add_u64 v[84:85], v[122:123], 0, v[142:143]
	v_lshl_add_u64 v[88:89], v[120:121], 0, v[144:145]
	v_lshl_add_u64 v[92:93], v[122:123], 0, v[144:145]
	v_lshl_add_u64 v[96:97], v[120:121], 0, v[146:147]
	v_lshl_add_u64 v[100:101], v[122:123], 0, v[146:147]
	v_lshl_add_u64 v[104:105], v[120:121], 0, v[148:149]
	v_lshl_add_u64 v[108:109], v[122:123], 0, v[148:149]
	v_lshl_add_u64 v[112:113], v[120:121], 0, v[150:151]
	v_lshl_add_u64 v[116:117], v[122:123], 0, v[150:151]
	v_lshl_add_u64 v[120:121], v[120:121], 0, v[152:153]
	v_lshl_add_u64 v[124:125], v[122:123], 0, v[152:153]
	global_load_dwordx4 v[64:67], v[64:65], off
	s_nop 0
	global_load_dwordx4 v[68:71], v[68:69], off
	s_nop 0
	global_load_dwordx4 v[72:75], v[72:73], off
	s_nop 0
	global_load_dwordx4 v[76:79], v[76:77], off
	s_nop 0
	global_load_dwordx4 v[80:83], v[80:81], off
	s_nop 0
	global_load_dwordx4 v[84:87], v[84:85], off
	s_nop 0
	global_load_dwordx4 v[88:91], v[88:89], off
	s_nop 0
	global_load_dwordx4 v[92:95], v[92:93], off
	s_nop 0
	global_load_dwordx4 v[96:99], v[96:97], off
	s_nop 0
	global_load_dwordx4 v[100:103], v[100:101], off
	s_nop 0
	global_load_dwordx4 v[104:107], v[104:105], off
	s_nop 0
	global_load_dwordx4 v[108:111], v[108:109], off
	s_nop 0
	global_load_dwordx4 v[112:115], v[112:113], off
	s_nop 0
	global_load_dwordx4 v[116:119], v[116:117], off
	s_nop 0
	global_load_dwordx4 v[120:123], v[120:121], off
	s_nop 0
	global_load_dwordx4 v[124:127], v[124:125], off
	v_mov_b32_e32 v216, v157
	v_mov_b32_e32 v217, v161
	v_mov_b32_e32 v212, v155
	v_mov_b32_e32 v213, v159
	v_mov_b32_e32 v214, v156
	v_mov_b32_e32 v215, v160
	v_pk_mul_f32 v[216:217], v[216:217], v[216:217]
	v_pk_mul_f32 v[212:213], v[212:213], v[212:213]
	v_pk_fma_f32 v[214:215], v[214:215], v[214:215], v[216:217]
	v_mov_b32_e32 v216, v154
	v_mov_b32_e32 v217, v158
	v_pk_fma_f32 v[212:213], v[216:217], v[216:217], v[212:213]
	v_mov_b32_e32 v191, v196
	v_pk_add_f32 v[212:213], v[212:213], v[214:215]
	v_mov_b32_e32 v193, v197
	v_pk_add_f32 v[212:213], v[212:213], v[212:213] op_sel:[0,1] op_sel_hi:[1,0]
	v_mov_b32_e32 v177, v195
	v_mov_b32_e32 v213, v194
	v_pk_add_f32 v[190:191], v[190:191], v[192:193]
	v_pk_add_f32 v[176:177], v[212:213], v[176:177]
	v_mov_b32_e32 v201, v210
	v_pk_add_f32 v[176:177], v[176:177], v[190:191]
	v_mov_b32_e32 v203, v211
	v_pk_add_f32 v[176:177], v[176:177], v[176:177] op_sel:[0,1] op_sel_hi:[1,0]
	v_mov_b32_e32 v199, v209
	v_mov_b32_e32 v177, v208
	v_pk_add_f32 v[190:191], v[200:201], v[202:203]
	v_pk_add_f32 v[176:177], v[176:177], v[198:199]
	s_nop 0
	v_pk_add_f32 v[176:177], v[176:177], v[190:191]
	s_nop 0
	v_add_f32_e32 v176, v176, v177
	ds_bpermute_b32 v177, v129, v176
	s_waitcnt lgkmcnt(0)
	v_add_f32_e32 v176, v176, v177
	ds_bpermute_b32 v177, v184, v176
	s_waitcnt lgkmcnt(0)
	v_add_f32_e32 v176, v176, v177
	ds_bpermute_b32 v177, v185, v176
	s_waitcnt lgkmcnt(0)
	v_add_f32_e32 v176, v176, v177
	ds_bpermute_b32 v177, v186, v176
	s_waitcnt lgkmcnt(0)
	v_add_f32_e32 v176, v176, v177
	ds_bpermute_b32 v177, v187, v176
	s_waitcnt lgkmcnt(0)
	v_add_f32_e32 v176, v176, v177
	ds_bpermute_b32 v177, v188, v176
	s_waitcnt lgkmcnt(0)
	v_add_f32_e32 v176, v176, v177
	v_fmamk_f32 v176, v176, 0x3a000000, v131
	v_mul_f32_e32 v177, 0x4b800000, v176
	v_cmp_gt_f32_e32 vcc, s22, v176
	s_nop 1
	v_cndmask_b32_e32 v176, v176, v177, vcc
	v_rsq_f32_e32 v176, v176
	s_nop 0
	v_mul_f32_e32 v177, 0x45800000, v176
	v_cndmask_b32_e32 v176, v176, v177, vcc
	v_pk_mul_f32 v[158:159], v[158:159], v[176:177] op_sel_hi:[1,0]
	v_pk_mul_f32 v[160:161], v[160:161], v[176:177] op_sel_hi:[1,0]
	v_pk_fma_f32 v[24:25], v[32:33], v[158:159], v[24:25]
	v_pk_fma_f32 v[26:27], v[34:35], v[160:161], v[26:27]
	v_pk_mul_f32 v[32:33], v[180:181], v[176:177] op_sel_hi:[1,0]
	v_pk_mul_f32 v[34:35], v[182:183], v[176:177] op_sel_hi:[1,0]
	v_pk_mul_f32 v[154:155], v[154:155], v[176:177] op_sel_hi:[1,0]
	v_pk_mul_f32 v[156:157], v[156:157], v[176:177] op_sel_hi:[1,0]
	s_waitcnt vmcnt(17)
	v_pk_fma_f32 v[6:7], v[62:63], v[34:35], v[6:7]
	v_pk_fma_f32 v[4:5], v[60:61], v[32:33], v[4:5]
	v_pk_mul_f32 v[32:33], v[204:205], v[176:177] op_sel_hi:[1,0]
	v_pk_mul_f32 v[34:35], v[206:207], v[176:177] op_sel_hi:[1,0]
	v_pk_mul_f32 v[162:163], v[162:163], v[176:177] op_sel_hi:[1,0]
	v_pk_mul_f32 v[164:165], v[164:165], v[176:177] op_sel_hi:[1,0]
	v_pk_mul_f32 v[166:167], v[166:167], v[176:177] op_sel_hi:[1,0]
	v_pk_mul_f32 v[168:169], v[168:169], v[176:177] op_sel_hi:[1,0]
	v_pk_mul_f32 v[170:171], v[170:171], v[176:177] op_sel_hi:[1,0]
	v_pk_mul_f32 v[172:173], v[172:173], v[176:177] op_sel_hi:[1,0]
	v_pk_mul_f32 v[174:175], v[174:175], v[176:177] op_sel_hi:[1,0]
	v_pk_mul_f32 v[178:179], v[178:179], v[176:177] op_sel_hi:[1,0]
	v_pk_fma_f32 v[30:31], v[38:39], v[156:157], v[30:31]
	v_pk_fma_f32 v[28:29], v[36:37], v[154:155], v[28:29]
	s_waitcnt vmcnt(16)
	v_pk_fma_f32 v[2:3], v[50:51], v[34:35], v[2:3]
	v_pk_fma_f32 v[0:1], v[48:49], v[32:33], v[0:1]
	v_pk_fma_f32 v[22:23], v[46:47], v[164:165], v[22:23]
	v_pk_fma_f32 v[20:21], v[44:45], v[162:163], v[20:21]
	v_pk_fma_f32 v[18:19], v[42:43], v[168:169], v[18:19]
	v_pk_fma_f32 v[16:17], v[40:41], v[166:167], v[16:17]
	v_pk_fma_f32 v[14:15], v[58:59], v[172:173], v[14:15]
	v_pk_fma_f32 v[12:13], v[56:57], v[170:171], v[12:13]
	v_pk_fma_f32 v[10:11], v[54:55], v[178:179], v[10:11]
	v_pk_fma_f32 v[8:9], v[52:53], v[174:175], v[8:9]
	global_store_dwordx4 v[136:137], v[28:31], off offset:-4096
	global_store_dwordx4 v[136:137], v[24:27], off offset:-3072
	global_store_dwordx4 v[136:137], v[20:23], off offset:-2048
	global_store_dwordx4 v[136:137], v[16:19], off offset:-1024
	global_store_dwordx4 v[136:137], v[12:15], off
	global_store_dwordx4 v[136:137], v[8:11], off offset:1024
	global_store_dwordx4 v[136:137], v[4:7], off offset:2048
	global_store_dwordx4 v[136:137], v[0:3], off offset:3072
	v_mov_b32_e32 v34, v29
	v_mov_b32_e32 v35, v25
	v_mov_b32_e32 v38, v31
	v_mov_b32_e32 v39, v27
	v_mov_b32_e32 v32, v28
	v_mov_b32_e32 v33, v24
	v_mov_b32_e32 v36, v30
	v_mov_b32_e32 v37, v26
	v_pk_mul_f32 v[40:41], v[22:23], v[22:23]
	v_pk_mul_f32 v[42:43], v[20:21], v[20:21]
	v_pk_mul_f32 v[34:35], v[34:35], v[34:35]
	v_pk_mul_f32 v[38:39], v[38:39], v[38:39]
	v_pk_mov_b32 v[58:59], v[42:43], v[40:41] op_sel:[1,0]
	v_mov_b32_e32 v43, v41
	v_pk_fma_f32 v[32:33], v[32:33], v[32:33], v[34:35]
	v_pk_fma_f32 v[34:35], v[36:37], v[36:37], v[38:39]
	v_mul_f32_e32 v44, v16, v16
	v_mul_f32_e32 v46, v18, v18
	v_pk_add_f32 v[36:37], v[58:59], v[42:43]
	v_pk_add_f32 v[32:33], v[32:33], v[34:35]
	v_pk_fma_f32 v[40:41], v[16:17], v[16:17], v[44:45] op_sel_hi:[1,1,0]
	v_pk_fma_f32 v[44:45], v[18:19], v[18:19], v[46:47] op_sel_hi:[1,1,0]
	v_pk_add_f32 v[34:35], v[36:37], v[36:37] op_sel_hi:[0,1]
	v_pk_add_f32 v[32:33], v[32:33], v[32:33] op_sel_hi:[0,1]
	v_pk_mul_f32 v[48:49], v[10:11], v[10:11]
	v_pk_mul_f32 v[50:51], v[8:9], v[8:9]
	v_mul_f32_e32 v40, v12, v12
	v_mul_f32_e32 v44, v13, v13
	v_mul_f32_e32 v34, v14, v14
	v_mul_f32_e32 v32, v15, v15
	v_pk_mov_b32 v[46:47], v[50:51], v[48:49] op_sel:[1,0]
	v_mov_b32_e32 v51, v49
	v_pk_add_f32 v[36:37], v[40:41], v[44:45]
	v_pk_add_f32 v[32:33], v[34:35], v[32:33]
	v_mul_f32_e32 v52, v4, v4
	v_mul_f32_e32 v54, v6, v6
	v_pk_add_f32 v[38:39], v[46:47], v[50:51]
	v_pk_add_f32 v[32:33], v[36:37], v[32:33]
	v_pk_fma_f32 v[48:49], v[4:5], v[4:5], v[52:53] op_sel_hi:[1,1,0]
	v_pk_fma_f32 v[52:53], v[6:7], v[6:7], v[54:55] op_sel_hi:[1,1,0]
	v_pk_add_f32 v[38:39], v[38:39], v[38:39] op_sel_hi:[0,1]
	v_pk_add_f32 v[32:33], v[32:33], v[32:33] op_sel_hi:[0,1]
	v_mul_f32_e32 v48, v0, v0
	v_mul_f32_e32 v52, v1, v1
	v_mul_f32_e32 v38, v2, v2
	v_mul_f32_e32 v32, v3, v3
	v_pk_add_f32 v[40:41], v[48:49], v[52:53]
	v_pk_add_f32 v[32:33], v[38:39], v[32:33]
	v_add_co_u32_e32 v56, vcc, s23, v134
	v_pk_add_f32 v[32:33], v[40:41], v[32:33]
	s_nop 0
	v_addc_co_u32_e32 v57, vcc, -1, v135, vcc
	v_add_f32_e32 v32, v32, v33
	ds_bpermute_b32 v33, v129, v32
	v_readfirstlane_b32 s83, v237
	s_lshl_b32 s83, s83, 1
	s_add_u32 s83, s83, s86
	s_add_u32 s83, s83, s94
	s_lshl_b32 s83, s83, 3
	s_sub_u32 s84, s83, s82
	s_mov_b32 s82, s83
	s_mov_b32 s85, 0
	s_mov_b32 s2, s84
	s_lshl_b64 s[6:7], s[84:85], 12
	s_lshl_b64 s[8:9], s[84:85], 13
	v_add_u32_e32 v130, s2, v130
	v_cmp_lt_i32_e32 vcc, s24, v130
	s_or_b64 s[10:11], vcc, s[10:11]
	v_lshl_add_u64 v[134:135], v[134:135], 0, s[6:7]
	s_waitcnt lgkmcnt(0)
	v_add_f32_e32 v32, v32, v33
	ds_bpermute_b32 v33, v184, v32
	v_lshl_add_u64 v[136:137], v[136:137], 0, s[8:9]
	s_waitcnt lgkmcnt(0)
	v_add_f32_e32 v32, v32, v33
	ds_bpermute_b32 v33, v185, v32
	s_waitcnt lgkmcnt(0)
	v_add_f32_e32 v32, v32, v33
	ds_bpermute_b32 v33, v186, v32
	s_waitcnt lgkmcnt(0)
	v_add_f32_e32 v32, v32, v33
	ds_bpermute_b32 v33, v187, v32
	s_waitcnt lgkmcnt(0)
	v_add_f32_e32 v32, v32, v33
	ds_bpermute_b32 v33, v188, v32
	s_waitcnt lgkmcnt(0)
	v_add_f32_e32 v32, v32, v33
	v_fmamk_f32 v32, v32, 0x3a000000, v131
	v_mul_f32_e32 v33, 0x4b800000, v32
	v_cmp_gt_f32_e32 vcc, s22, v32
	s_nop 1
	v_cndmask_b32_e32 v32, v32, v33, vcc
	v_rsq_f32_e32 v32, v32
	s_nop 0
	v_mul_f32_e32 v33, 0x45800000, v32
	v_cndmask_b32_e32 v32, v32, v33, vcc
	v_pk_mul_f32 v[28:29], v[28:29], v[32:33] op_sel_hi:[1,0]
	v_pk_mul_f32 v[30:31], v[30:31], v[32:33] op_sel_hi:[1,0]
	v_pk_mul_f32 v[24:25], v[24:25], v[32:33] op_sel_hi:[1,0]
	v_pk_mul_f32 v[26:27], v[26:27], v[32:33] op_sel_hi:[1,0]
	v_pk_mul_f32 v[20:21], v[20:21], v[32:33] op_sel_hi:[1,0]
	v_pk_mul_f32 v[22:23], v[22:23], v[32:33] op_sel_hi:[1,0]
	v_pk_mul_f32 v[16:17], v[16:17], v[32:33] op_sel_hi:[1,0]
	v_pk_mul_f32 v[18:19], v[18:19], v[32:33] op_sel_hi:[1,0]
	v_pk_mul_f32 v[12:13], v[12:13], v[32:33] op_sel_hi:[1,0]
	v_pk_mul_f32 v[14:15], v[14:15], v[32:33] op_sel_hi:[1,0]
	v_pk_mul_f32 v[8:9], v[8:9], v[32:33] op_sel_hi:[1,0]
	v_pk_mul_f32 v[10:11], v[10:11], v[32:33] op_sel_hi:[1,0]
	v_pk_mul_f32 v[4:5], v[4:5], v[32:33] op_sel_hi:[1,0]
	v_pk_mul_f32 v[6:7], v[6:7], v[32:33] op_sel_hi:[1,0]
	v_pk_mul_f32 v[0:1], v[0:1], v[32:33] op_sel_hi:[1,0]
	v_pk_mul_f32 v[2:3], v[2:3], v[32:33] op_sel_hi:[1,0]
	s_waitcnt vmcnt(22)
	v_pk_fma_f32 v[30:31], v[66:67], v[30:31], v[70:71]
	v_pk_fma_f32 v[28:29], v[64:65], v[28:29], v[68:69]
	s_waitcnt vmcnt(20)
	v_pk_fma_f32 v[26:27], v[74:75], v[26:27], v[78:79]
	v_pk_fma_f32 v[24:25], v[72:73], v[24:25], v[76:77]
	s_waitcnt vmcnt(18)
	v_pk_fma_f32 v[22:23], v[82:83], v[22:23], v[86:87]
	v_pk_fma_f32 v[20:21], v[80:81], v[20:21], v[84:85]
	s_waitcnt vmcnt(16)
	v_pk_fma_f32 v[18:19], v[90:91], v[18:19], v[94:95]
	v_pk_fma_f32 v[16:17], v[88:89], v[16:17], v[92:93]
	s_waitcnt vmcnt(14)
	v_pk_fma_f32 v[14:15], v[98:99], v[14:15], v[102:103]
	v_pk_fma_f32 v[12:13], v[96:97], v[12:13], v[100:101]
	s_waitcnt vmcnt(12)
	v_pk_fma_f32 v[10:11], v[106:107], v[10:11], v[110:111]
	v_pk_fma_f32 v[8:9], v[104:105], v[8:9], v[108:109]
	s_waitcnt vmcnt(10)
	v_pk_fma_f32 v[6:7], v[114:115], v[6:7], v[118:119]
	v_pk_fma_f32 v[4:5], v[112:113], v[4:5], v[116:117]
	s_waitcnt vmcnt(8)
	v_pk_fma_f32 v[2:3], v[122:123], v[2:3], v[126:127]
	v_pk_fma_f32 v[0:1], v[120:121], v[0:1], v[124:125]
	v_cvt_pk_bf16_f32 v28, v28, v29
	v_cvt_pk_bf16_f32 v29, v30, v31
	v_cvt_pk_bf16_f32 v24, v24, v25
	v_cvt_pk_bf16_f32 v25, v26, v27
	v_cvt_pk_bf16_f32 v20, v20, v21
	v_cvt_pk_bf16_f32 v21, v22, v23
	v_cvt_pk_bf16_f32 v16, v16, v17
	v_cvt_pk_bf16_f32 v17, v18, v19
	v_cvt_pk_bf16_f32 v12, v12, v13
	v_cvt_pk_bf16_f32 v13, v14, v15
	v_cvt_pk_bf16_f32 v8, v8, v9
	v_cvt_pk_bf16_f32 v9, v10, v11
	v_cvt_pk_bf16_f32 v4, v4, v5
	v_cvt_pk_bf16_f32 v5, v6, v7
	v_cvt_pk_bf16_f32 v0, v0, v1
	v_cvt_pk_bf16_f32 v1, v2, v3
	global_store_dwordx2 v[56:57], v[28:29], off offset:-3584
	global_store_dwordx2 v[56:57], v[24:25], off offset:-3072
	global_store_dwordx2 v[56:57], v[20:21], off offset:-2560
	global_store_dwordx2 v[56:57], v[16:17], off offset:-2048
	global_store_dwordx2 v[56:57], v[12:13], off offset:-1536
	global_store_dwordx2 v[56:57], v[8:9], off offset:-1024
	global_store_dwordx2 v[56:57], v[4:5], off offset:-512
	global_store_dwordx2 v[56:57], v[0:1], off
	s_andn2_b64 exec, exec, s[10:11]
	s_cbranch_execnz .LBB0_1625

.LBB0_1830:
	s_mov_b64 s[80:81], exec
	s_mov_b64 exec, 1
	v_mov_b32_e32 v237, 1
	global_atomic_add v237, v236, v237, s[50:51] sc0
	s_mov_b64 exec, s[80:81]
	global_load_dwordx4 v[28:31], v[70:71], off offset:-4096
	global_load_dwordx4 v[24:27], v[70:71], off offset:-3072
	global_load_dwordx4 v[20:23], v[70:71], off offset:-2048
	global_load_dwordx4 v[16:19], v[70:71], off offset:-1024
	global_load_dwordx4 v[12:15], v[70:71], off
	global_load_dwordx4 v[8:11], v[70:71], off offset:1024
	global_load_dwordx4 v[4:7], v[70:71], off offset:2048
	global_load_dwordx4 v[0:3], v[70:71], off offset:3072
	v_add_u32_e32 v33, 0xffffe000, v64
	v_lshrrev_b32_e32 v33, 3, v33
	v_ashrrev_i32_e32 v32, 12, v64
	v_add_u32_e32 v33, 2, v33
	v_cmp_gt_i32_e32 vcc, s1, v64
	s_nop 1
	v_cndmask_b32_e32 v32, v33, v32, vcc
	v_mad_i64_i32 v[32:33], s[16:17], v32, s10, v[72:73]
	v_add_co_u32_e32 v50, vcc, s11, v68
	v_lshl_add_u64 v[48:49], v[32:33], 0, s[8:9]
	s_nop 0
	v_addc_co_u32_e32 v51, vcc, -1, v69, vcc
	v_add_co_u32_e32 v60, vcc, s12, v68
	v_lshl_add_u64 v[40:41], v[48:49], 0, v[66:67]
	s_nop 0
	v_addc_co_u32_e32 v61, vcc, -1, v69, vcc
	v_add_co_u32_e32 v62, vcc, s13, v68
	v_lshl_add_u64 v[42:43], v[48:49], 0, v[74:75]
	v_lshl_add_u64 v[52:53], v[48:49], 0, v[76:77]
	v_lshl_add_u64 v[54:55], v[48:49], 0, v[78:79]
	v_addc_co_u32_e32 v63, vcc, -1, v69, vcc
	global_load_dwordx4 v[36:39], v[40:41], off
	global_load_dwordx4 v[32:35], v[42:43], off
	global_load_dwordx2 v[90:91], v[50:51], off offset:-3584 nt
	global_load_dwordx2 v[102:103], v[50:51], off offset:-3072 nt
	global_load_dwordx2 v[114:115], v[50:51], off offset:-2560 nt
	global_load_dwordx2 v[126:127], v[50:51], off offset:-2048 nt
	global_load_dwordx2 v[100:101], v[60:61], off offset:-3584 nt
	global_load_dwordx2 v[112:113], v[60:61], off offset:-3072 nt
	global_load_dwordx2 v[116:117], v[60:61], off offset:-2560 nt
	global_load_dwordx2 v[128:129], v[60:61], off offset:-2048 nt
	global_load_dwordx2 v[136:137], v[62:63], off offset:-3584 nt
	global_load_dwordx2 v[138:139], v[62:63], off offset:-3072 nt
	global_load_dwordx2 v[140:141], v[62:63], off offset:-2560 nt
	global_load_dwordx2 v[142:143], v[62:63], off offset:-2048 nt
	global_load_dwordx2 v[144:145], v[68:69], off offset:-3584 nt
	global_load_dwordx2 v[146:147], v[68:69], off offset:-3072 nt
	global_load_dwordx2 v[148:149], v[68:69], off offset:-2560 nt
	global_load_dwordx2 v[150:151], v[68:69], off offset:-2048 nt
	global_load_dwordx4 v[44:47], v[52:53], off
	global_load_dwordx4 v[40:43], v[54:55], off
	v_lshl_add_u64 v[52:53], v[48:49], 0, v[80:81]
	v_lshl_add_u64 v[54:55], v[48:49], 0, v[82:83]
	global_load_dwordx4 v[56:59], v[52:53], off
	s_nop 0
	global_load_dwordx4 v[52:55], v[54:55], off
	s_nop 0
	global_load_dwordx2 v[152:153], v[50:51], off offset:-1536 nt
	global_load_dwordx2 v[118:119], v[50:51], off offset:-1024 nt
	global_load_dwordx2 v[104:105], v[50:51], off offset:-512 nt
	global_load_dwordx2 v[96:97], v[50:51], off nt
	global_load_dwordx2 v[154:155], v[60:61], off offset:-1536 nt
	global_load_dwordx2 v[124:125], v[60:61], off offset:-1024 nt
	global_load_dwordx2 v[110:111], v[60:61], off offset:-512 nt
	global_load_dwordx2 v[98:99], v[60:61], off nt
	global_load_dwordx2 v[156:157], v[62:63], off offset:-1536 nt
	global_load_dwordx2 v[120:121], v[62:63], off offset:-1024 nt
	global_load_dwordx2 v[106:107], v[62:63], off offset:-512 nt
	global_load_dwordx2 v[92:93], v[62:63], off nt
	global_load_dwordx2 v[158:159], v[68:69], off offset:-1536 nt
	global_load_dwordx2 v[122:123], v[68:69], off offset:-1024 nt
	global_load_dwordx2 v[108:109], v[68:69], off offset:-512 nt
	global_load_dwordx2 v[94:95], v[68:69], off nt
	v_lshl_add_u64 v[88:89], v[48:49], 0, v[84:85]
	v_lshl_add_u64 v[48:49], v[48:49], 0, v[86:87]
	global_load_dwordx4 v[60:63], v[88:89], off
	s_nop 0
	global_load_dwordx4 v[48:51], v[48:49], off
	s_waitcnt vmcnt(37)
	v_lshlrev_b32_e32 v88, 16, v90
	v_and_b32_e32 v89, 0xffff0000, v90
	s_waitcnt vmcnt(33)
	v_lshlrev_b32_e32 v160, 16, v100
	v_and_b32_e32 v161, 0xffff0000, v100
	v_lshlrev_b32_e32 v90, 16, v91
	v_and_b32_e32 v91, 0xffff0000, v91
	v_lshlrev_b32_e32 v100, 16, v101
	v_and_b32_e32 v101, 0xffff0000, v101
	v_pk_add_f32 v[88:89], v[88:89], v[160:161]
	s_waitcnt vmcnt(29)
	v_lshlrev_b32_e32 v160, 16, v136
	v_and_b32_e32 v161, 0xffff0000, v136
	v_pk_add_f32 v[90:91], v[90:91], v[100:101]
	v_lshlrev_b32_e32 v100, 16, v137
	v_and_b32_e32 v101, 0xffff0000, v137
	s_waitcnt vmcnt(25)
	v_lshlrev_b32_e32 v136, 16, v145
	v_and_b32_e32 v137, 0xffff0000, v145
	v_pk_add_f32 v[100:101], v[100:101], v[136:137]
	v_lshlrev_b32_e32 v136, 16, v112
	v_pk_add_f32 v[90:91], v[90:91], v[100:101]
	v_lshlrev_b32_e32 v100, 16, v102
	v_and_b32_e32 v101, 0xffff0000, v102
	v_and_b32_e32 v137, 0xffff0000, v112
	v_lshlrev_b32_e32 v162, 16, v144
	v_and_b32_e32 v163, 0xffff0000, v144
	v_pk_add_f32 v[100:101], v[100:101], v[136:137]
	v_lshlrev_b32_e32 v136, 16, v138
	v_and_b32_e32 v137, 0xffff0000, v138
	s_waitcnt vmcnt(24)
	v_lshlrev_b32_e32 v144, 16, v146
	v_and_b32_e32 v145, 0xffff0000, v146
	v_pk_add_f32 v[136:137], v[136:137], v[144:145]
	v_lshlrev_b32_e32 v102, 16, v103
	v_and_b32_e32 v103, 0xffff0000, v103
	v_lshlrev_b32_e32 v112, 16, v113
	v_and_b32_e32 v113, 0xffff0000, v113
	v_pk_add_f32 v[160:161], v[160:161], v[162:163]
	v_pk_add_f32 v[100:101], v[100:101], v[136:137]
	v_pk_add_f32 v[102:103], v[102:103], v[112:113]
	v_lshlrev_b32_e32 v112, 16, v139
	v_and_b32_e32 v113, 0xffff0000, v139
	v_lshlrev_b32_e32 v136, 16, v147
	v_and_b32_e32 v137, 0xffff0000, v147
	v_pk_add_f32 v[88:89], v[88:89], v[160:161]
	v_pk_add_f32 v[112:113], v[112:113], v[136:137]
	v_mov_b32_e32 v136, v89
	v_pk_add_f32 v[102:103], v[102:103], v[112:113]
	v_mov_b32_e32 v137, v101
	v_mov_b32_e32 v112, v88
	v_mov_b32_e32 v113, v100
	v_pk_mul_f32 v[136:137], v[136:137], v[136:137]
	v_mov_b32_e32 v138, v91
	v_mov_b32_e32 v139, v103
	v_pk_fma_f32 v[112:113], v[112:113], v[112:113], v[136:137]
	v_mov_b32_e32 v136, v90
	v_mov_b32_e32 v137, v102
	v_pk_mul_f32 v[138:139], v[138:139], v[138:139]
	s_waitcnt vmcnt(23)
	v_lshlrev_b32_e32 v144, 16, v148
	v_pk_fma_f32 v[136:137], v[136:137], v[136:137], v[138:139]
	v_lshlrev_b32_e32 v138, 16, v116
	v_pk_add_f32 v[112:113], v[112:113], v[136:137]
	v_and_b32_e32 v139, 0xffff0000, v116
	v_pk_add_f32 v[136:137], v[112:113], v[112:113] op_sel:[0,1] op_sel_hi:[1,0]
	v_lshlrev_b32_e32 v112, 16, v114
	v_and_b32_e32 v113, 0xffff0000, v114
	v_pk_add_f32 v[112:113], v[112:113], v[138:139]
	v_lshlrev_b32_e32 v138, 16, v140
	v_and_b32_e32 v139, 0xffff0000, v140
	v_and_b32_e32 v145, 0xffff0000, v148
	v_pk_add_f32 v[138:139], v[138:139], v[144:145]
	v_lshlrev_b32_e32 v114, 16, v115
	v_and_b32_e32 v115, 0xffff0000, v115
	v_lshlrev_b32_e32 v116, 16, v117
	v_and_b32_e32 v117, 0xffff0000, v117
	v_pk_add_f32 v[112:113], v[112:113], v[138:139]
	v_pk_add_f32 v[114:115], v[114:115], v[116:117]
	v_lshlrev_b32_e32 v116, 16, v141
	v_and_b32_e32 v117, 0xffff0000, v141
	v_lshlrev_b32_e32 v138, 16, v149
	v_and_b32_e32 v139, 0xffff0000, v149
	v_pk_add_f32 v[116:117], v[116:117], v[138:139]
	v_mov_b32_e32 v138, v113
	v_pk_add_f32 v[114:115], v[114:115], v[116:117]
	v_mov_b32_e32 v116, v112
	v_mov_b32_e32 v139, v115
	v_mov_b32_e32 v117, v114
	v_pk_mul_f32 v[138:139], v[138:139], v[138:139]
	v_lshlrev_b32_e32 v140, 16, v128
	v_pk_fma_f32 v[116:117], v[116:117], v[116:117], v[138:139]
	v_and_b32_e32 v141, 0xffff0000, v128
	v_pk_add_f32 v[138:139], v[116:117], v[116:117] op_sel:[0,1] op_sel_hi:[1,0]
	v_lshlrev_b32_e32 v116, 16, v126
	v_and_b32_e32 v117, 0xffff0000, v126
	v_pk_add_f32 v[116:117], v[116:117], v[140:141]
	v_lshlrev_b32_e32 v140, 16, v142
	v_and_b32_e32 v141, 0xffff0000, v142
	s_waitcnt vmcnt(22)
	v_lshlrev_b32_e32 v144, 16, v150
	v_and_b32_e32 v145, 0xffff0000, v150
	v_pk_add_f32 v[140:141], v[140:141], v[144:145]
	v_lshlrev_b32_e32 v126, 16, v127
	v_and_b32_e32 v127, 0xffff0000, v127
	v_lshlrev_b32_e32 v128, 16, v129
	v_and_b32_e32 v129, 0xffff0000, v129
	v_pk_add_f32 v[116:117], v[116:117], v[140:141]
	v_pk_add_f32 v[126:127], v[126:127], v[128:129]
	v_lshlrev_b32_e32 v128, 16, v143
	v_and_b32_e32 v129, 0xffff0000, v143
	v_lshlrev_b32_e32 v140, 16, v151
	v_and_b32_e32 v141, 0xffff0000, v151
	v_pk_add_f32 v[128:129], v[128:129], v[140:141]
	s_waitcnt vmcnt(13)
	v_lshlrev_b32_e32 v144, 16, v154
	v_pk_add_f32 v[126:127], v[126:127], v[128:129]
	v_mul_f32_e32 v128, v117, v117
	v_pk_fma_f32 v[140:141], v[116:117], v[116:117], v[128:129] op_sel_hi:[1,1,0]
	v_mul_f32_e32 v128, v127, v127
	v_pk_fma_f32 v[142:143], v[126:127], v[126:127], v[128:129] op_sel_hi:[1,1,0]
	v_lshlrev_b32_e32 v128, 16, v152
	v_and_b32_e32 v129, 0xffff0000, v152
	v_and_b32_e32 v145, 0xffff0000, v154
	v_pk_add_f32 v[128:129], v[128:129], v[144:145]
	s_waitcnt vmcnt(9)
	v_lshlrev_b32_e32 v144, 16, v156
	v_and_b32_e32 v145, 0xffff0000, v156
	s_waitcnt vmcnt(5)
	v_lshlrev_b32_e32 v146, 16, v158
	v_and_b32_e32 v147, 0xffff0000, v158
	v_pk_add_f32 v[144:145], v[144:145], v[146:147]
	v_lshlrev_b32_e32 v146, 16, v155
	v_pk_add_f32 v[128:129], v[128:129], v[144:145]
	v_lshlrev_b32_e32 v144, 16, v153
	v_and_b32_e32 v145, 0xffff0000, v153
	v_and_b32_e32 v147, 0xffff0000, v155
	v_pk_add_f32 v[144:145], v[144:145], v[146:147]
	v_lshlrev_b32_e32 v146, 16, v157
	v_and_b32_e32 v147, 0xffff0000, v157
	v_lshlrev_b32_e32 v148, 16, v159
	v_and_b32_e32 v149, 0xffff0000, v159
	v_pk_add_f32 v[146:147], v[146:147], v[148:149]
	s_nop 0
	v_pk_add_f32 v[144:145], v[144:145], v[146:147]
	v_pk_mul_f32 v[146:147], v[128:129], v[128:129]
	v_pk_mul_f32 v[148:149], v[144:145], v[144:145]
	v_mov_b32_e32 v137, v146
	v_mov_b32_e32 v139, v147
	v_mov_b32_e32 v141, v148
	v_mov_b32_e32 v143, v149
	v_pk_add_f32 v[136:137], v[136:137], v[138:139]
	v_pk_add_f32 v[138:139], v[140:141], v[142:143]
	v_lshlrev_b32_e32 v140, 16, v124
	v_pk_add_f32 v[136:137], v[136:137], v[138:139]
	v_lshlrev_b32_e32 v138, 16, v118
	v_and_b32_e32 v139, 0xffff0000, v118
	v_and_b32_e32 v141, 0xffff0000, v124
	v_pk_add_f32 v[138:139], v[138:139], v[140:141]
	v_lshlrev_b32_e32 v140, 16, v120
	v_and_b32_e32 v141, 0xffff0000, v120
	s_waitcnt vmcnt(4)
	v_lshlrev_b32_e32 v142, 16, v122
	v_and_b32_e32 v143, 0xffff0000, v122
	v_lshlrev_b32_e32 v118, 16, v119
	v_and_b32_e32 v119, 0xffff0000, v119
	v_lshlrev_b32_e32 v124, 16, v125
	v_and_b32_e32 v125, 0xffff0000, v125
	v_lshlrev_b32_e32 v120, 16, v121
	v_and_b32_e32 v121, 0xffff0000, v121
	v_lshlrev_b32_e32 v122, 16, v123
	v_and_b32_e32 v123, 0xffff0000, v123
	v_pk_add_f32 v[140:141], v[140:141], v[142:143]
	v_pk_add_f32 v[118:119], v[118:119], v[124:125]
	v_pk_add_f32 v[120:121], v[120:121], v[122:123]
	v_pk_add_f32 v[138:139], v[138:139], v[140:141]
	v_pk_add_f32 v[118:119], v[118:119], v[120:121]
	v_mov_b32_e32 v122, v139
	v_mov_b32_e32 v123, v119
	v_mov_b32_e32 v120, v138
	v_mov_b32_e32 v121, v118
	v_pk_mul_f32 v[122:123], v[122:123], v[122:123]
	v_lshlrev_b32_e32 v124, 16, v110
	v_pk_fma_f32 v[120:121], v[120:121], v[120:121], v[122:123]
	v_lshlrev_b32_e32 v122, 16, v104
	v_and_b32_e32 v123, 0xffff0000, v104
	v_and_b32_e32 v125, 0xffff0000, v110
	v_pk_add_f32 v[122:123], v[122:123], v[124:125]
	v_lshlrev_b32_e32 v124, 16, v106
	v_and_b32_e32 v125, 0xffff0000, v106
	s_waitcnt vmcnt(3)
	v_lshlrev_b32_e32 v140, 16, v108
	v_and_b32_e32 v141, 0xffff0000, v108
	v_pk_add_f32 v[124:125], v[124:125], v[140:141]
	v_lshlrev_b32_e32 v104, 16, v105
	v_and_b32_e32 v105, 0xffff0000, v105
	v_lshlrev_b32_e32 v110, 16, v111
	v_and_b32_e32 v111, 0xffff0000, v111
	v_pk_add_f32 v[122:123], v[122:123], v[124:125]
	v_pk_add_f32 v[104:105], v[104:105], v[110:111]
	v_lshlrev_b32_e32 v106, 16, v107
	v_and_b32_e32 v107, 0xffff0000, v107
	v_lshlrev_b32_e32 v108, 16, v109
	v_and_b32_e32 v109, 0xffff0000, v109
	v_lshlrev_b32_e32 v110, 16, v96
	v_and_b32_e32 v111, 0xffff0000, v96
	v_lshlrev_b32_e32 v124, 16, v98
	v_and_b32_e32 v125, 0xffff0000, v98
	v_pk_add_f32 v[106:107], v[106:107], v[108:109]
	v_pk_add_f32 v[110:111], v[110:111], v[124:125]
	v_lshlrev_b32_e32 v124, 16, v92
	v_and_b32_e32 v125, 0xffff0000, v92
	s_waitcnt vmcnt(2)
	v_lshlrev_b32_e32 v140, 16, v94
	v_and_b32_e32 v141, 0xffff0000, v94
	v_lshlrev_b32_e32 v96, 16, v97
	v_and_b32_e32 v97, 0xffff0000, v97
	v_lshlrev_b32_e32 v98, 16, v99
	v_and_b32_e32 v99, 0xffff0000, v99
	v_lshlrev_b32_e32 v92, 16, v93
	v_and_b32_e32 v93, 0xffff0000, v93
	v_lshlrev_b32_e32 v94, 16, v95
	v_and_b32_e32 v95, 0xffff0000, v95
	v_pk_add_f32 v[104:105], v[104:105], v[106:107]
	v_pk_add_f32 v[124:125], v[124:125], v[140:141]
	v_pk_add_f32 v[96:97], v[96:97], v[98:99]
	v_pk_add_f32 v[92:93], v[92:93], v[94:95]
	v_mul_f32_e32 v106, v123, v123
	v_mul_f32_e32 v108, v105, v105
	v_pk_add_f32 v[110:111], v[110:111], v[124:125]
	v_pk_add_f32 v[92:93], v[96:97], v[92:93]
	v_pk_add_f32 v[136:137], v[136:137], v[136:137] op_sel:[0,1] op_sel_hi:[1,0]
	v_pk_add_f32 v[120:121], v[120:121], v[120:121] op_sel:[0,1] op_sel_hi:[1,0]
	v_pk_fma_f32 v[106:107], v[122:123], v[122:123], v[106:107] op_sel_hi:[1,1,0]
	v_pk_fma_f32 v[108:109], v[104:105], v[104:105], v[108:109] op_sel_hi:[1,1,0]
	v_pk_mul_f32 v[94:95], v[110:111], v[110:111]
	v_pk_mul_f32 v[96:97], v[92:93], v[92:93]
	v_mov_b32_e32 v137, v94
	v_mov_b32_e32 v121, v95
	v_mov_b32_e32 v107, v96
	v_mov_b32_e32 v109, v97
	v_pk_add_f32 v[94:95], v[136:137], v[120:121]
	v_pk_add_f32 v[96:97], v[106:107], v[108:109]
	s_nop 0
	v_pk_add_f32 v[94:95], v[94:95], v[96:97]
	s_nop 0
	v_add_f32_e32 v94, v94, v95
	ds_bpermute_b32 v95, v130, v94
	s_waitcnt lgkmcnt(0)
	v_add_f32_e32 v94, v94, v95
	ds_bpermute_b32 v95, v131, v94
	s_waitcnt lgkmcnt(0)
	v_add_f32_e32 v94, v94, v95
	ds_bpermute_b32 v95, v132, v94
	s_waitcnt lgkmcnt(0)
	v_add_f32_e32 v94, v94, v95
	ds_bpermute_b32 v95, v133, v94
	s_waitcnt lgkmcnt(0)
	v_add_f32_e32 v94, v94, v95
	ds_bpermute_b32 v95, v134, v94
	s_waitcnt lgkmcnt(0)
	v_add_f32_e32 v94, v94, v95
	ds_bpermute_b32 v95, v135, v94
	s_waitcnt lgkmcnt(0)
	v_add_f32_e32 v94, v94, v95
	v_fmamk_f32 v94, v94, 0x3a000000, v65
	v_mul_f32_e32 v95, 0x4b800000, v94
	v_cmp_gt_f32_e32 vcc, s14, v94
	s_nop 1
	v_cndmask_b32_e32 v94, v94, v95, vcc
	v_rsq_f32_e32 v94, v94
	s_nop 0
	v_mul_f32_e32 v95, 0x45800000, v94
	v_cndmask_b32_e32 v94, v94, v95, vcc
	v_pk_mul_f32 v[88:89], v[88:89], v[94:95] op_sel_hi:[1,0]
	v_pk_mul_f32 v[90:91], v[90:91], v[94:95] op_sel_hi:[1,0]
	v_pk_mul_f32 v[106:107], v[116:117], v[94:95] op_sel_hi:[1,0]
	v_pk_mul_f32 v[116:117], v[138:139], v[94:95] op_sel_hi:[1,0]
	v_pk_mul_f32 v[118:119], v[118:119], v[94:95] op_sel_hi:[1,0]
	v_pk_mul_f32 v[96:97], v[100:101], v[94:95] op_sel_hi:[1,0]
	v_pk_mul_f32 v[98:99], v[102:103], v[94:95] op_sel_hi:[1,0]
	v_pk_mul_f32 v[100:101], v[112:113], v[94:95] op_sel_hi:[1,0]
	v_pk_mul_f32 v[102:103], v[114:115], v[94:95] op_sel_hi:[1,0]
	v_pk_mul_f32 v[108:109], v[126:127], v[94:95] op_sel_hi:[1,0]
	v_pk_mul_f32 v[112:113], v[128:129], v[94:95] op_sel_hi:[1,0]
	v_pk_mul_f32 v[114:115], v[144:145], v[94:95] op_sel_hi:[1,0]
	v_pk_fma_f32 v[30:31], v[38:39], v[90:91], v[30:31]
	v_pk_fma_f32 v[28:29], v[36:37], v[88:89], v[28:29]
	v_pk_fma_f32 v[10:11], v[54:55], v[118:119], v[10:11]
	v_pk_fma_f32 v[8:9], v[52:53], v[116:117], v[8:9]
	v_pk_fma_f32 v[26:27], v[34:35], v[98:99], v[26:27]
	v_pk_fma_f32 v[24:25], v[32:33], v[96:97], v[24:25]
	v_pk_fma_f32 v[22:23], v[46:47], v[102:103], v[22:23]
	v_pk_fma_f32 v[20:21], v[44:45], v[100:101], v[20:21]
	v_pk_fma_f32 v[18:19], v[42:43], v[108:109], v[18:19]
	v_pk_fma_f32 v[16:17], v[40:41], v[106:107], v[16:17]
	v_pk_fma_f32 v[14:15], v[58:59], v[114:115], v[14:15]
	v_pk_fma_f32 v[12:13], v[56:57], v[112:113], v[12:13]
	global_store_dwordx4 v[70:71], v[28:31], off offset:-4096 nt
	global_store_dwordx4 v[70:71], v[24:27], off offset:-3072 nt
	global_store_dwordx4 v[70:71], v[20:23], off offset:-2048 nt
	global_store_dwordx4 v[70:71], v[16:19], off offset:-1024 nt
	global_store_dwordx4 v[70:71], v[12:15], off nt
	global_store_dwordx4 v[70:71], v[8:11], off offset:1024 nt
	s_nop 1
	v_pk_mul_f32 v[8:9], v[122:123], v[94:95] op_sel_hi:[1,0]
	v_pk_mul_f32 v[10:11], v[104:105], v[94:95] op_sel_hi:[1,0]
	s_waitcnt vmcnt(7)
	v_pk_fma_f32 v[4:5], v[60:61], v[8:9], v[4:5]
	v_pk_fma_f32 v[6:7], v[62:63], v[10:11], v[6:7]
	global_store_dwordx4 v[70:71], v[4:7], off offset:2048 nt
	s_nop 1
	v_pk_mul_f32 v[4:5], v[110:111], v[94:95] op_sel_hi:[1,0]
	v_pk_mul_f32 v[6:7], v[92:93], v[94:95] op_sel_hi:[1,0]
	s_waitcnt vmcnt(7)
	v_pk_fma_f32 v[0:1], v[48:49], v[4:5], v[0:1]
	v_pk_fma_f32 v[2:3], v[50:51], v[6:7], v[2:3]
	global_store_dwordx4 v[70:71], v[0:3], off offset:3072 nt
	s_waitcnt vmcnt(8)
	v_readfirstlane_b32 s83, v237
	s_lshl_b32 s83, s83, 1
	s_add_u32 s83, s83, s86
	s_add_u32 s83, s83, s94
	s_lshl_b32 s83, s83, 3
	s_sub_u32 s84, s83, s82
	s_mov_b32 s82, s83
	s_mov_b32 s85, 0
	s_mov_b32 s0, s84
	s_lshl_b64 s[2:3], s[84:85], 12
	s_lshl_b64 s[4:5], s[84:85], 13
	v_add_u32_e32 v64, s0, v64
	v_cmp_lt_i32_e32 vcc, s15, v64
	v_lshl_add_u64 v[68:69], v[68:69], 0, s[2:3]
	s_or_b64 s[6:7], vcc, s[6:7]
	v_lshl_add_u64 v[70:71], v[70:71], 0, s[4:5]
	s_andn2_b64 exec, exec, s[6:7]
	s_cbranch_execnz .LBB0_1830
